# v076 + GEMM K-loops: the wait state between each m0 write and its LDS-DMA load is filled by a moved ds_read_b128 instead of s_nop 0 (40 nops removed)
# baseline (speedup 1.0000x reference)
; #define PG8_STAGE(bufoff, gbase, voff) do { _Pragma("unroll") for (int _i = 0; _i < 2; ++_i) \
;         __builtin_amdgcn_global_load_lds((const unsigned*)((const char*)(gbase) + (voff)[_i]), (PG8_LAS unsigned*)(lds + (bufoff) + ldsw + _i * 8192), 16, 0, 0); } while (0)
; #define PG8_LDA(dst, b, h) do { _Pragma("unroll") for (int m = 0; m < 4; ++m) _Pragma("unroll") for (int k = 0; k < 2; ++k) dst[m][k] = *(const PG8_LAS bf16x8*)(lds + PG8_SA(b, h) + aoff + m * 2048 + k * 1024); } while (0)
; #define PG8_LDB(dst, b, h) do { _Pragma("unroll") for (int n = 0; n < 2; ++n) _Pragma("unroll") for (int k = 0; k < 2; ++k) dst[n][k] = *(const PG8_LAS bf16x8*)(lds + PG8_SB(b, h) + boff + n * 2048 + k * 1024); } while (0)
; #define PG8_MMA(ai, bj, At, Bt) do { __builtin_amdgcn_s_setprio(1); _Pragma("unroll") for (int m = 0; m < 4; ++m) _Pragma("unroll") for (int n = 0; n < 2; ++n) _Pragma("unroll") for (int k = 0; k < 2; ++k) \
;         acc[ai][bj][m][n] = __builtin_amdgcn_mfma_f32_16x16x32_bf16(Bt[n][k], At[m][k], acc[ai][bj][m][n], 0, 0, 0); __builtin_amdgcn_s_setprio(0); } while (0)
; #define PG8_WAIT_V(n) asm volatile("s_waitcnt vmcnt(" #n ")" ::: "memory")
; #define PG8_WAIT_L(n) asm volatile("s_waitcnt lgkmcnt(" #n ")" ::: "memory")
; #define PG8_BAR __builtin_amdgcn_s_barrier()
; #define PG8_SCHED __builtin_amdgcn_sched_barrier(0)
; template <class Epi, class Sched, bool ALIGN_EPI = false, bool SP2 = false>
; __device__ __forceinline__ void gemm_phase(PG8_LAS unsigned char* lds, const Gemm g, const Sched& S, const Epi& E) {
;     ...
;             PG8_LDB(B0, 0, 0); PG8_LDB(B1, 0, 1); PG8_SCHED; PG8_LDA(At, 0, 0); PG8_STAGE(PG8_SA(1, 1), a1 + hstep, voffA);
;             PG8_WAIT_V(8); PG8_WAIT_L(0); PG8_BAR; PG8_MMA(0, 0, At, B0); PG8_MMA(0, 1, At, B1); PG8_BAR; PG8_SCHED;
;             PG8_LDA(At, 0, 1); PG8_STAGE(PG8_SB(0, 0), b2, voffB); PG8_STAGE(PG8_SB(0, 1), b2 + hstep, voffB); PG8_STAGE(PG8_SA(0, 0), a2, voffA);
;             PG8_WAIT_V(8); PG8_WAIT_L(0); PG8_BAR; PG8_MMA(1, 0, At, B0); PG8_MMA(1, 1, At, B1); PG8_BAR; PG8_SCHED;
.LBB0_119:
	ds_read_b128 v[56:59], v167
	ds_read_b128 v[60:63], v167 offset:1024
	ds_read_b128 v[136:139], v167 offset:2048
	ds_read_b128 v[158:161], v167 offset:3072
	ds_read_b128 v[170:173], v168
	ds_read_b128 v[174:177], v168 offset:1024
	ds_read_b128 v[178:181], v168 offset:2048
	ds_read_b128 v[182:185], v168 offset:3072
	s_add_u32 s26, s24, 0xfffc0080
	s_addc_u32 s27, s25, -1
	s_cmp_eq_u32 s50, 12
	s_cselect_b32 s29, s5, s27
	s_cselect_b32 s28, s7, s26
	s_cselect_b32 s27, s17, s37
	s_cselect_b32 s26, s19, s36
	s_add_u32 vcc_lo, s26, 0x80
	s_addc_u32 vcc_hi, s27, 0
	s_add_u32 s100, s28, 0x80
	s_addc_u32 s101, s29, 0
	s_add_i32 m0, s31, 0xc000
	ds_read_b128 v[186:189], v169
	ds_read_b128 v[194:197], v169 offset:1024
	ds_read_b128 v[198:201], v169 offset:2048
	ds_read_b128 v[202:205], v169 offset:3072
	ds_read_b128 v[206:209], v169 offset:4096
	ds_read_b128 v[210:213], v169 offset:5120
	ds_read_b128 v[214:217], v169 offset:6144
	global_load_lds_dwordx4 v150, s[24:25]
	s_add_i32 m0, s31, 0xe000
	ds_read_b128 v[218:221], v169 offset:7168
	global_load_lds_dwordx4 v152, s[24:25]
	s_waitcnt vmcnt(8)
	s_waitcnt lgkmcnt(0)
	s_barrier
	s_setprio 1
	s_waitcnt lgkmcnt(0)
	v_mfma_f32_16x16x32_bf16 v[132:135], v[56:59], v[186:189], v[132:135]
	v_mfma_f32_16x16x32_bf16 v[128:131], v[136:139], v[186:189], v[128:131]
	v_mfma_f32_16x16x32_bf16 v[116:119], v[56:59], v[198:201], v[116:119]
	v_mfma_f32_16x16x32_bf16 v[112:115], v[136:139], v[198:201], v[112:115]
	v_mfma_f32_16x16x32_bf16 v[100:103], v[56:59], v[206:209], v[100:103]
	v_mfma_f32_16x16x32_bf16 v[96:99], v[136:139], v[206:209], v[96:99]
	v_mfma_f32_16x16x32_bf16 v[84:87], v[56:59], v[214:217], v[84:87]
	v_mfma_f32_16x16x32_bf16 v[80:83], v[136:139], v[214:217], v[80:83]
	v_mfma_f32_16x16x32_bf16 v[132:135], v[60:63], v[194:197], v[132:135]
	v_mfma_f32_16x16x32_bf16 v[128:131], v[158:161], v[194:197], v[128:131]
	v_mfma_f32_16x16x32_bf16 v[116:119], v[60:63], v[202:205], v[116:119]
	v_mfma_f32_16x16x32_bf16 v[112:115], v[158:161], v[202:205], v[112:115]
	v_mfma_f32_16x16x32_bf16 v[100:103], v[60:63], v[210:213], v[100:103]
	v_mfma_f32_16x16x32_bf16 v[96:99], v[158:161], v[210:213], v[96:99]
	v_mfma_f32_16x16x32_bf16 v[84:87], v[60:63], v[218:221], v[84:87]
	v_mfma_f32_16x16x32_bf16 v[80:83], v[158:161], v[218:221], v[80:83]
	s_setprio 0
	s_setprio 1
	v_mfma_f32_16x16x32_bf16 v[124:127], v[170:173], v[186:189], v[124:127]
	v_mfma_f32_16x16x32_bf16 v[120:123], v[178:181], v[186:189], v[120:123]
	v_mfma_f32_16x16x32_bf16 v[108:111], v[170:173], v[198:201], v[108:111]
	v_mfma_f32_16x16x32_bf16 v[104:107], v[178:181], v[198:201], v[104:107]
	v_mfma_f32_16x16x32_bf16 v[92:95], v[170:173], v[206:209], v[92:95]
	v_mfma_f32_16x16x32_bf16 v[88:91], v[178:181], v[206:209], v[88:91]
	v_mfma_f32_16x16x32_bf16 v[76:79], v[170:173], v[214:217], v[76:79]
	v_mfma_f32_16x16x32_bf16 v[72:75], v[178:181], v[214:217], v[72:75]
	v_mfma_f32_16x16x32_bf16 v[124:127], v[174:177], v[194:197], v[124:127]
	v_mfma_f32_16x16x32_bf16 v[120:123], v[182:185], v[194:197], v[120:123]
	v_mfma_f32_16x16x32_bf16 v[108:111], v[174:177], v[202:205], v[108:111]
	v_mfma_f32_16x16x32_bf16 v[104:107], v[182:185], v[202:205], v[104:107]
	v_mfma_f32_16x16x32_bf16 v[92:95], v[174:177], v[210:213], v[92:95]
	v_mfma_f32_16x16x32_bf16 v[88:91], v[182:185], v[210:213], v[88:91]
	v_mfma_f32_16x16x32_bf16 v[76:79], v[174:177], v[218:221], v[76:79]
	v_mfma_f32_16x16x32_bf16 v[72:75], v[182:185], v[218:221], v[72:75]
	s_setprio 0
	s_barrier
	s_add_i32 s51, s88, s58
	s_mov_b32 m0, s51
	ds_read_b128 v[186:189], v169 offset:16384
	ds_read_b128 v[194:197], v169 offset:17408
	ds_read_b128 v[198:201], v169 offset:18432
	ds_read_b128 v[202:205], v169 offset:19456
	global_load_lds_dwordx4 v142, s[26:27]
	s_add_i32 m0, s51, 0x2000
	s_add_u32 s76, s26, 0x40000
	s_addc_u32 s77, s27, 0
	s_add_i32 s51, s89, s58
	global_load_lds_dwordx4 v146, s[26:27]
	s_mov_b32 m0, s51
	ds_read_b128 v[218:221], v169 offset:23552
	global_load_lds_dwordx4 v142, s[76:77]
	s_add_i32 m0, s51, 0x2000
	ds_read_b128 v[214:217], v169 offset:22528
	global_load_lds_dwordx4 v146, s[76:77]
	s_mov_b32 m0, s31
	ds_read_b128 v[210:213], v169 offset:21504
	global_load_lds_dwordx4 v140, s[28:29]
	s_mov_b32 m0, s0
	ds_read_b128 v[206:209], v169 offset:20480
	global_load_lds_dwordx4 v144, s[28:29]
	s_waitcnt vmcnt(8)
	s_waitcnt lgkmcnt(0)
	s_barrier
	s_setprio 1
	s_waitcnt lgkmcnt(0)
	v_mfma_f32_16x16x32_bf16 v[68:71], v[56:59], v[186:189], v[68:71]
	v_mfma_f32_16x16x32_bf16 v[64:67], v[136:139], v[186:189], v[64:67]
	v_mfma_f32_16x16x32_bf16 v[44:47], v[56:59], v[198:201], v[44:47]
	v_mfma_f32_16x16x32_bf16 v[40:43], v[136:139], v[198:201], v[40:43]
	v_mfma_f32_16x16x32_bf16 v[28:31], v[56:59], v[206:209], v[28:31]
	v_mfma_f32_16x16x32_bf16 v[24:27], v[136:139], v[206:209], v[24:27]
	v_mfma_f32_16x16x32_bf16 v[12:15], v[56:59], v[214:217], v[12:15]
	v_mfma_f32_16x16x32_bf16 v[8:11], v[136:139], v[214:217], v[8:11]
	v_mfma_f32_16x16x32_bf16 v[68:71], v[60:63], v[194:197], v[68:71]
	v_mfma_f32_16x16x32_bf16 v[64:67], v[158:161], v[194:197], v[64:67]
	v_mfma_f32_16x16x32_bf16 v[44:47], v[60:63], v[202:205], v[44:47]
	v_mfma_f32_16x16x32_bf16 v[40:43], v[158:161], v[202:205], v[40:43]
	v_mfma_f32_16x16x32_bf16 v[28:31], v[60:63], v[210:213], v[28:31]
	v_mfma_f32_16x16x32_bf16 v[24:27], v[158:161], v[210:213], v[24:27]
	v_mfma_f32_16x16x32_bf16 v[12:15], v[60:63], v[218:221], v[12:15]
	v_mfma_f32_16x16x32_bf16 v[8:11], v[158:161], v[218:221], v[8:11]
	s_setprio 0
	s_setprio 1
	v_mfma_f32_16x16x32_bf16 v[52:55], v[170:173], v[186:189], v[52:55]
	v_mfma_f32_16x16x32_bf16 v[48:51], v[178:181], v[186:189], v[48:51]
	v_mfma_f32_16x16x32_bf16 v[36:39], v[170:173], v[198:201], v[36:39]
	v_mfma_f32_16x16x32_bf16 v[32:35], v[178:181], v[198:201], v[32:35]
	v_mfma_f32_16x16x32_bf16 v[20:23], v[170:173], v[206:209], v[20:23]
	v_mfma_f32_16x16x32_bf16 v[16:19], v[178:181], v[206:209], v[16:19]
	v_mfma_f32_16x16x32_bf16 v[4:7], v[170:173], v[214:217], v[4:7]
	v_mfma_f32_16x16x32_bf16 v[0:3], v[178:181], v[214:217], v[0:3]
	v_mfma_f32_16x16x32_bf16 v[52:55], v[174:177], v[194:197], v[52:55]
	v_mfma_f32_16x16x32_bf16 v[48:51], v[182:185], v[194:197], v[48:51]
	v_mfma_f32_16x16x32_bf16 v[36:39], v[174:177], v[202:205], v[36:39]
	v_mfma_f32_16x16x32_bf16 v[32:35], v[182:185], v[202:205], v[32:35]
	v_mfma_f32_16x16x32_bf16 v[20:23], v[174:177], v[210:213], v[20:23]
	v_mfma_f32_16x16x32_bf16 v[16:19], v[182:185], v[210:213], v[16:19]
	v_mfma_f32_16x16x32_bf16 v[4:7], v[174:177], v[218:221], v[4:7]
	v_mfma_f32_16x16x32_bf16 v[0:3], v[182:185], v[218:221], v[0:3]
	s_setprio 0
	s_barrier
; #define PG8_STAGE(bufoff, gbase, voff) do { _Pragma("unroll") for (int _i = 0; _i < 2; ++_i) \
;         __builtin_amdgcn_global_load_lds((const unsigned*)((const char*)(gbase) + (voff)[_i]), (PG8_LAS unsigned*)(lds + (bufoff) + ldsw + _i * 8192), 16, 0, 0); } while (0)
; #define PG8_LDA(dst, b, h) do { _Pragma("unroll") for (int m = 0; m < 4; ++m) _Pragma("unroll") for (int k = 0; k < 2; ++k) dst[m][k] = *(const PG8_LAS bf16x8*)(lds + PG8_SA(b, h) + aoff + m * 2048 + k * 1024); } while (0)
; #define PG8_LDB(dst, b, h) do { _Pragma("unroll") for (int n = 0; n < 2; ++n) _Pragma("unroll") for (int k = 0; k < 2; ++k) dst[n][k] = *(const PG8_LAS bf16x8*)(lds + PG8_SB(b, h) + boff + n * 2048 + k * 1024); } while (0)
; #define PG8_MMA(ai, bj, At, Bt) do { __builtin_amdgcn_s_setprio(1); _Pragma("unroll") for (int m = 0; m < 4; ++m) _Pragma("unroll") for (int n = 0; n < 2; ++n) _Pragma("unroll") for (int k = 0; k < 2; ++k) \
;         acc[ai][bj][m][n] = __builtin_amdgcn_mfma_f32_16x16x32_bf16(Bt[n][k], At[m][k], acc[ai][bj][m][n], 0, 0, 0); __builtin_amdgcn_s_setprio(0); } while (0)
; #define PG8_WAIT_V(n) asm volatile("s_waitcnt vmcnt(" #n ")" ::: "memory")
; #define PG8_WAIT_L(n) asm volatile("s_waitcnt lgkmcnt(" #n ")" ::: "memory")
; #define PG8_BAR __builtin_amdgcn_s_barrier()
; #define PG8_SCHED __builtin_amdgcn_sched_barrier(0)
; template <class Epi, class Sched, bool ALIGN_EPI = false, bool SP2 = false>
; __device__ __forceinline__ void gemm_phase(PG8_LAS unsigned char* lds, const Gemm g, const Sched& S, const Epi& E) {
;     ...
;             PG8_LDB(B0, 1, 0); PG8_LDB(B1, 1, 1); PG8_SCHED; PG8_LDA(At, 1, 0); PG8_STAGE(PG8_SA(0, 1), a2 + hstep, voffA);
;             PG8_WAIT_V(8); PG8_WAIT_L(0); PG8_BAR; PG8_MMA(0, 0, At, B0); PG8_MMA(0, 1, At, B1); PG8_BAR; PG8_SCHED;
;             PG8_LDA(At, 1, 1); PG8_STAGE(PG8_SB(1, 0), b3, voffB); PG8_STAGE(PG8_SB(1, 1), b3 + hstep, voffB); PG8_STAGE(PG8_SA(1, 0), a3, voffA);
;             PG8_WAIT_V(8); PG8_WAIT_L(0); PG8_BAR; PG8_MMA(1, 0, At, B0); PG8_MMA(1, 1, At, B1); PG8_BAR; PG8_SCHED;
	s_add_i32 s51, 0, 0x18000
	s_add_i32 s76, 0, 0x1c000
	v_add_u32_e32 v158, s51, v165
	v_add_u32_e32 v182, s76, v165
	ds_read_b128 v[56:59], v158
	ds_read_b128 v[60:63], v158 offset:1024
	ds_read_b128 v[136:139], v158 offset:2048
	ds_read_b128 v[158:161], v158 offset:3072
	ds_read_b128 v[170:173], v182
	ds_read_b128 v[174:177], v182 offset:1024
	ds_read_b128 v[178:181], v182 offset:2048
	ds_read_b128 v[182:185], v182 offset:3072
	s_add_u32 s28, s28, 0x40000
	s_addc_u32 s29, s29, 0
	s_mov_b32 m0, s1
	ds_read_b128 v[186:189], v169 offset:32768
	ds_read_b128 v[194:197], v169 offset:33792
	ds_read_b128 v[198:201], v169 offset:34816
	ds_read_b128 v[202:205], v169 offset:35840
	ds_read_b128 v[206:209], v169 offset:36864
	ds_read_b128 v[210:213], v169 offset:37888
	ds_read_b128 v[214:217], v169 offset:38912
	global_load_lds_dwordx4 v140, s[28:29]
	s_mov_b32 m0, s38
	ds_read_b128 v[218:221], v169 offset:39936
	global_load_lds_dwordx4 v144, s[28:29]
	s_waitcnt vmcnt(8)
	s_waitcnt lgkmcnt(0)
	s_barrier
	s_setprio 1
	s_waitcnt lgkmcnt(0)
	v_mfma_f32_16x16x32_bf16 v[132:135], v[56:59], v[186:189], v[132:135]
	v_mfma_f32_16x16x32_bf16 v[128:131], v[136:139], v[186:189], v[128:131]
	v_mfma_f32_16x16x32_bf16 v[116:119], v[56:59], v[198:201], v[116:119]
	v_mfma_f32_16x16x32_bf16 v[112:115], v[136:139], v[198:201], v[112:115]
	v_mfma_f32_16x16x32_bf16 v[100:103], v[56:59], v[206:209], v[100:103]
	v_mfma_f32_16x16x32_bf16 v[96:99], v[136:139], v[206:209], v[96:99]
	v_mfma_f32_16x16x32_bf16 v[84:87], v[56:59], v[214:217], v[84:87]
	v_mfma_f32_16x16x32_bf16 v[80:83], v[136:139], v[214:217], v[80:83]
	v_mfma_f32_16x16x32_bf16 v[132:135], v[60:63], v[194:197], v[132:135]
	v_mfma_f32_16x16x32_bf16 v[128:131], v[158:161], v[194:197], v[128:131]
	v_mfma_f32_16x16x32_bf16 v[116:119], v[60:63], v[202:205], v[116:119]
	v_mfma_f32_16x16x32_bf16 v[112:115], v[158:161], v[202:205], v[112:115]
	v_mfma_f32_16x16x32_bf16 v[100:103], v[60:63], v[210:213], v[100:103]
	v_mfma_f32_16x16x32_bf16 v[96:99], v[158:161], v[210:213], v[96:99]
	v_mfma_f32_16x16x32_bf16 v[84:87], v[60:63], v[218:221], v[84:87]
	v_mfma_f32_16x16x32_bf16 v[80:83], v[158:161], v[218:221], v[80:83]
	s_setprio 0
	s_setprio 1
	v_mfma_f32_16x16x32_bf16 v[124:127], v[170:173], v[186:189], v[124:127]
	v_mfma_f32_16x16x32_bf16 v[120:123], v[178:181], v[186:189], v[120:123]
	v_mfma_f32_16x16x32_bf16 v[108:111], v[170:173], v[198:201], v[108:111]
	v_mfma_f32_16x16x32_bf16 v[104:107], v[178:181], v[198:201], v[104:107]
	v_mfma_f32_16x16x32_bf16 v[92:95], v[170:173], v[206:209], v[92:95]
	v_mfma_f32_16x16x32_bf16 v[88:91], v[178:181], v[206:209], v[88:91]
	v_mfma_f32_16x16x32_bf16 v[76:79], v[170:173], v[214:217], v[76:79]
	v_mfma_f32_16x16x32_bf16 v[72:75], v[178:181], v[214:217], v[72:75]
	v_mfma_f32_16x16x32_bf16 v[124:127], v[174:177], v[194:197], v[124:127]
	v_mfma_f32_16x16x32_bf16 v[120:123], v[182:185], v[194:197], v[120:123]
	v_mfma_f32_16x16x32_bf16 v[108:111], v[174:177], v[202:205], v[108:111]
	v_mfma_f32_16x16x32_bf16 v[104:107], v[182:185], v[202:205], v[104:107]
	v_mfma_f32_16x16x32_bf16 v[92:95], v[174:177], v[210:213], v[92:95]
	v_mfma_f32_16x16x32_bf16 v[88:91], v[182:185], v[210:213], v[88:91]
	v_mfma_f32_16x16x32_bf16 v[76:79], v[174:177], v[218:221], v[76:79]
	v_mfma_f32_16x16x32_bf16 v[72:75], v[182:185], v[218:221], v[72:75]
	s_setprio 0
	s_barrier
	s_add_i32 s28, s51, s58
	s_mov_b32 m0, s28
	ds_read_b128 v[186:189], v169 offset:49152
	ds_read_b128 v[194:197], v169 offset:50176
	ds_read_b128 v[198:201], v169 offset:51200
	ds_read_b128 v[202:205], v169 offset:52224
	global_load_lds_dwordx4 v142, vcc
	s_add_i32 m0, s28, 0x2000
	s_add_u32 s26, s26, 0x40080
	s_addc_u32 s27, s27, 0
	s_add_i32 s28, s76, s58
	global_load_lds_dwordx4 v146, vcc
	s_mov_b32 m0, s28
	ds_read_b128 v[218:221], v169 offset:56320
	global_load_lds_dwordx4 v142, s[26:27]
	s_add_i32 m0, s28, 0x2000
	ds_read_b128 v[214:217], v169 offset:55296
	global_load_lds_dwordx4 v146, s[26:27]
	s_mov_b32 m0, s42
	ds_read_b128 v[210:213], v169 offset:54272
	global_load_lds_dwordx4 v140, s[100:101]
	s_mov_b32 m0, s59
	ds_read_b128 v[206:209], v169 offset:53248
	global_load_lds_dwordx4 v144, s[100:101]
	s_waitcnt vmcnt(8)
	s_waitcnt lgkmcnt(0)
	s_barrier
	s_setprio 1
	s_waitcnt lgkmcnt(0)
	v_mfma_f32_16x16x32_bf16 v[68:71], v[56:59], v[186:189], v[68:71]
	v_mfma_f32_16x16x32_bf16 v[64:67], v[136:139], v[186:189], v[64:67]
	v_mfma_f32_16x16x32_bf16 v[44:47], v[56:59], v[198:201], v[44:47]
	v_mfma_f32_16x16x32_bf16 v[40:43], v[136:139], v[198:201], v[40:43]
	v_mfma_f32_16x16x32_bf16 v[28:31], v[56:59], v[206:209], v[28:31]
	v_mfma_f32_16x16x32_bf16 v[24:27], v[136:139], v[206:209], v[24:27]
	v_mfma_f32_16x16x32_bf16 v[12:15], v[56:59], v[214:217], v[12:15]
	v_mfma_f32_16x16x32_bf16 v[8:11], v[136:139], v[214:217], v[8:11]
	v_mfma_f32_16x16x32_bf16 v[68:71], v[60:63], v[194:197], v[68:71]
	v_mfma_f32_16x16x32_bf16 v[64:67], v[158:161], v[194:197], v[64:67]
	v_mfma_f32_16x16x32_bf16 v[44:47], v[60:63], v[202:205], v[44:47]
	v_mfma_f32_16x16x32_bf16 v[40:43], v[158:161], v[202:205], v[40:43]
	v_mfma_f32_16x16x32_bf16 v[28:31], v[60:63], v[210:213], v[28:31]
	v_mfma_f32_16x16x32_bf16 v[24:27], v[158:161], v[210:213], v[24:27]
	v_mfma_f32_16x16x32_bf16 v[12:15], v[60:63], v[218:221], v[12:15]
	v_mfma_f32_16x16x32_bf16 v[8:11], v[158:161], v[218:221], v[8:11]
	s_setprio 0
	s_setprio 1
	v_mfma_f32_16x16x32_bf16 v[52:55], v[170:173], v[186:189], v[52:55]
	v_mfma_f32_16x16x32_bf16 v[48:51], v[178:181], v[186:189], v[48:51]
	v_mfma_f32_16x16x32_bf16 v[36:39], v[170:173], v[198:201], v[36:39]
	v_mfma_f32_16x16x32_bf16 v[32:35], v[178:181], v[198:201], v[32:35]
	v_mfma_f32_16x16x32_bf16 v[20:23], v[170:173], v[206:209], v[20:23]
	v_mfma_f32_16x16x32_bf16 v[16:19], v[178:181], v[206:209], v[16:19]
	v_mfma_f32_16x16x32_bf16 v[4:7], v[170:173], v[214:217], v[4:7]
	v_mfma_f32_16x16x32_bf16 v[0:3], v[178:181], v[214:217], v[0:3]
	v_mfma_f32_16x16x32_bf16 v[52:55], v[174:177], v[194:197], v[52:55]
	v_mfma_f32_16x16x32_bf16 v[48:51], v[182:185], v[194:197], v[48:51]
	v_mfma_f32_16x16x32_bf16 v[36:39], v[174:177], v[202:205], v[36:39]
	v_mfma_f32_16x16x32_bf16 v[32:35], v[182:185], v[202:205], v[32:35]
	v_mfma_f32_16x16x32_bf16 v[20:23], v[174:177], v[210:213], v[20:23]
	v_mfma_f32_16x16x32_bf16 v[16:19], v[182:185], v[210:213], v[16:19]
	v_mfma_f32_16x16x32_bf16 v[4:7], v[174:177], v[218:221], v[4:7]
	v_mfma_f32_16x16x32_bf16 v[0:3], v[182:185], v[218:221], v[0:3]
	s_setprio 0
	s_barrier
	s_add_i32 s50, s50, 2
	s_add_u32 s24, s24, 0x100
	s_addc_u32 s25, s25, 0
	s_add_u32 s36, s36, 0x100
	s_addc_u32 s37, s37, 0
	s_cmp_gt_u32 s50, 13
	s_cbranch_scc0 .LBB0_119
	s_and_b64 vcc, exec, s[12:13]
	s_cbranch_vccz .LBB0_122
	s_barrier

; #define PG8_STAGE(bufoff, gbase, voff) do { _Pragma("unroll") for (int _i = 0; _i < 2; ++_i) \
;         __builtin_amdgcn_global_load_lds((const unsigned*)((const char*)(gbase) + (voff)[_i]), (PG8_LAS unsigned*)(lds + (bufoff) + ldsw + _i * 8192), 16, 0, 0); } while (0)
; #define PG8_LDA(dst, b, h) do { _Pragma("unroll") for (int m = 0; m < 4; ++m) _Pragma("unroll") for (int k = 0; k < 2; ++k) dst[m][k] = *(const PG8_LAS bf16x8*)(lds + PG8_SA(b, h) + aoff + m * 2048 + k * 1024); } while (0)
; #define PG8_LDB(dst, b, h) do { _Pragma("unroll") for (int n = 0; n < 2; ++n) _Pragma("unroll") for (int k = 0; k < 2; ++k) dst[n][k] = *(const PG8_LAS bf16x8*)(lds + PG8_SB(b, h) + boff + n * 2048 + k * 1024); } while (0)
; #define PG8_MMA(ai, bj, At, Bt) do { __builtin_amdgcn_s_setprio(1); _Pragma("unroll") for (int m = 0; m < 4; ++m) _Pragma("unroll") for (int n = 0; n < 2; ++n) _Pragma("unroll") for (int k = 0; k < 2; ++k) \
;         acc[ai][bj][m][n] = __builtin_amdgcn_mfma_f32_16x16x32_bf16(Bt[n][k], At[m][k], acc[ai][bj][m][n], 0, 0, 0); __builtin_amdgcn_s_setprio(0); } while (0)
; #define PG8_WAIT_V(n) asm volatile("s_waitcnt vmcnt(" #n ")" ::: "memory")
; #define PG8_WAIT_L(n) asm volatile("s_waitcnt lgkmcnt(" #n ")" ::: "memory")
; #define PG8_BAR __builtin_amdgcn_s_barrier()
; #define PG8_SCHED __builtin_amdgcn_sched_barrier(0)
; template <class Epi, class Sched, bool ALIGN_EPI = false, bool SP2 = false>
; __device__ __forceinline__ void gemm_phase(PG8_LAS unsigned char* lds, const Gemm g, const Sched& S, const Epi& E) {
;     ...
;             PG8_LDB(B0, 0, 0); PG8_LDB(B1, 0, 1); PG8_SCHED; PG8_LDA(At, 0, 0); PG8_STAGE(PG8_SA(1, 1), a1 + hstep, voffA);
;             PG8_WAIT_V(8); PG8_WAIT_L(0); PG8_BAR; PG8_MMA(0, 0, At, B0); PG8_MMA(0, 1, At, B1); PG8_BAR; PG8_SCHED;
;             PG8_LDA(At, 0, 1); PG8_STAGE(PG8_SB(0, 0), b2, voffB); PG8_STAGE(PG8_SB(0, 1), b2 + hstep, voffB); PG8_STAGE(PG8_SA(0, 0), a2, voffA);
;             PG8_WAIT_V(8); PG8_WAIT_L(0); PG8_BAR; PG8_MMA(1, 0, At, B0); PG8_MMA(1, 1, At, B1); PG8_BAR; PG8_SCHED;
.LBB0_413:
	ds_read_b128 v[144:147], v151
	ds_read_b128 v[154:157], v151 offset:1024
	ds_read_b128 v[158:161], v151 offset:2048
	ds_read_b128 v[162:165], v151 offset:3072
	ds_read_b128 v[166:169], v152
	ds_read_b128 v[170:173], v152 offset:1024
	ds_read_b128 v[174:177], v152 offset:2048
	ds_read_b128 v[178:181], v152 offset:3072
	s_add_u32 s36, s34, 0xfffc0080
	s_addc_u32 s37, s35, -1
	s_cmp_eq_u32 s64, 12
	s_cselect_b32 s41, s23, s37
	s_cselect_b32 s40, s29, s36
	s_cselect_b32 s37, s21, s63
	s_cselect_b32 s36, s59, s62
	s_add_u32 vcc_lo, s36, 0x80
	s_addc_u32 vcc_hi, s37, 0
	s_add_u32 s100, s40, 0x80
	s_addc_u32 s101, s41, 0
	s_add_i32 m0, s1, 0xc000
	ds_read_b128 v[182:185], v153
	ds_read_b128 v[186:189], v153 offset:1024
	ds_read_b128 v[194:197], v153 offset:2048
	ds_read_b128 v[198:201], v153 offset:3072
	ds_read_b128 v[202:205], v153 offset:4096
	ds_read_b128 v[206:209], v153 offset:5120
	ds_read_b128 v[210:213], v153 offset:6144
	global_load_lds_dwordx4 v136, s[34:35]
	s_add_i32 m0, s1, 0xe000
	ds_read_b128 v[214:217], v153 offset:7168
	global_load_lds_dwordx4 v138, s[34:35]
	s_waitcnt vmcnt(8)
	s_waitcnt lgkmcnt(0)
	s_barrier
	s_setprio 1
	s_waitcnt lgkmcnt(0)
	v_mfma_f32_16x16x32_bf16 v[124:127], v[144:147], v[182:185], v[124:127]
	v_mfma_f32_16x16x32_bf16 v[120:123], v[158:161], v[182:185], v[120:123]
	v_mfma_f32_16x16x32_bf16 v[108:111], v[144:147], v[194:197], v[108:111]
	v_mfma_f32_16x16x32_bf16 v[104:107], v[158:161], v[194:197], v[104:107]
	v_mfma_f32_16x16x32_bf16 v[92:95], v[144:147], v[202:205], v[92:95]
	v_mfma_f32_16x16x32_bf16 v[88:91], v[158:161], v[202:205], v[88:91]
	v_mfma_f32_16x16x32_bf16 v[76:79], v[144:147], v[210:213], v[76:79]
	v_mfma_f32_16x16x32_bf16 v[72:75], v[158:161], v[210:213], v[72:75]
	v_mfma_f32_16x16x32_bf16 v[124:127], v[154:157], v[186:189], v[124:127]
	v_mfma_f32_16x16x32_bf16 v[120:123], v[162:165], v[186:189], v[120:123]
	v_mfma_f32_16x16x32_bf16 v[108:111], v[154:157], v[198:201], v[108:111]
	v_mfma_f32_16x16x32_bf16 v[104:107], v[162:165], v[198:201], v[104:107]
	v_mfma_f32_16x16x32_bf16 v[92:95], v[154:157], v[206:209], v[92:95]
	v_mfma_f32_16x16x32_bf16 v[88:91], v[162:165], v[206:209], v[88:91]
	v_mfma_f32_16x16x32_bf16 v[76:79], v[154:157], v[214:217], v[76:79]
	v_mfma_f32_16x16x32_bf16 v[72:75], v[162:165], v[214:217], v[72:75]
	s_setprio 0
	s_setprio 1
	v_mfma_f32_16x16x32_bf16 v[116:119], v[166:169], v[182:185], v[116:119]
	v_mfma_f32_16x16x32_bf16 v[112:115], v[174:177], v[182:185], v[112:115]
	v_mfma_f32_16x16x32_bf16 v[100:103], v[166:169], v[194:197], v[100:103]
	v_mfma_f32_16x16x32_bf16 v[96:99], v[174:177], v[194:197], v[96:99]
	v_mfma_f32_16x16x32_bf16 v[84:87], v[166:169], v[202:205], v[84:87]
	v_mfma_f32_16x16x32_bf16 v[80:83], v[174:177], v[202:205], v[80:83]
	v_mfma_f32_16x16x32_bf16 v[68:71], v[166:169], v[210:213], v[68:71]
	v_mfma_f32_16x16x32_bf16 v[64:67], v[174:177], v[210:213], v[64:67]
	v_mfma_f32_16x16x32_bf16 v[116:119], v[170:173], v[186:189], v[116:119]
	v_mfma_f32_16x16x32_bf16 v[112:115], v[178:181], v[186:189], v[112:115]
	v_mfma_f32_16x16x32_bf16 v[100:103], v[170:173], v[198:201], v[100:103]
	v_mfma_f32_16x16x32_bf16 v[96:99], v[178:181], v[198:201], v[96:99]
	v_mfma_f32_16x16x32_bf16 v[84:87], v[170:173], v[206:209], v[84:87]
	v_mfma_f32_16x16x32_bf16 v[80:83], v[178:181], v[206:209], v[80:83]
	v_mfma_f32_16x16x32_bf16 v[68:71], v[170:173], v[214:217], v[68:71]
	v_mfma_f32_16x16x32_bf16 v[64:67], v[178:181], v[214:217], v[64:67]
	s_setprio 0
	s_barrier
	s_add_i32 s65, s50, s0
	s_mov_b32 m0, s65
	ds_read_b128 v[182:185], v153 offset:16384
	ds_read_b128 v[186:189], v153 offset:17408
	ds_read_b128 v[194:197], v153 offset:18432
	ds_read_b128 v[198:201], v153 offset:19456
	global_load_lds_dwordx4 v130, s[36:37]
	s_add_i32 m0, s65, 0x2000
	s_add_u32 s66, s36, 0x40000
	s_addc_u32 s67, s37, 0
	s_add_i32 s65, s51, s0
	global_load_lds_dwordx4 v134, s[36:37]
	s_mov_b32 m0, s65
	ds_read_b128 v[214:217], v153 offset:23552
	global_load_lds_dwordx4 v130, s[66:67]
	s_add_i32 m0, s65, 0x2000
	ds_read_b128 v[210:213], v153 offset:22528
	global_load_lds_dwordx4 v134, s[66:67]
	s_mov_b32 m0, s1
	ds_read_b128 v[206:209], v153 offset:21504
	global_load_lds_dwordx4 v128, s[40:41]
	s_mov_b32 m0, s31
	ds_read_b128 v[202:205], v153 offset:20480
	global_load_lds_dwordx4 v132, s[40:41]
	s_waitcnt vmcnt(8)
	s_waitcnt lgkmcnt(0)
	s_barrier
	s_setprio 1
	s_waitcnt lgkmcnt(0)
	v_mfma_f32_16x16x32_bf16 v[60:63], v[144:147], v[182:185], v[60:63]
	v_mfma_f32_16x16x32_bf16 v[56:59], v[158:161], v[182:185], v[56:59]
	v_mfma_f32_16x16x32_bf16 v[44:47], v[144:147], v[194:197], v[44:47]
	v_mfma_f32_16x16x32_bf16 v[40:43], v[158:161], v[194:197], v[40:43]
	v_mfma_f32_16x16x32_bf16 v[28:31], v[144:147], v[202:205], v[28:31]
	v_mfma_f32_16x16x32_bf16 v[24:27], v[158:161], v[202:205], v[24:27]
	v_mfma_f32_16x16x32_bf16 v[12:15], v[144:147], v[210:213], v[12:15]
	v_mfma_f32_16x16x32_bf16 v[8:11], v[158:161], v[210:213], v[8:11]
	v_mfma_f32_16x16x32_bf16 v[60:63], v[154:157], v[186:189], v[60:63]
	v_mfma_f32_16x16x32_bf16 v[56:59], v[162:165], v[186:189], v[56:59]
	v_mfma_f32_16x16x32_bf16 v[44:47], v[154:157], v[198:201], v[44:47]
	v_mfma_f32_16x16x32_bf16 v[40:43], v[162:165], v[198:201], v[40:43]
	v_mfma_f32_16x16x32_bf16 v[28:31], v[154:157], v[206:209], v[28:31]
	v_mfma_f32_16x16x32_bf16 v[24:27], v[162:165], v[206:209], v[24:27]
	v_mfma_f32_16x16x32_bf16 v[12:15], v[154:157], v[214:217], v[12:15]
	v_mfma_f32_16x16x32_bf16 v[8:11], v[162:165], v[214:217], v[8:11]
	s_setprio 0
	s_setprio 1
	v_mfma_f32_16x16x32_bf16 v[52:55], v[166:169], v[182:185], v[52:55]
	v_mfma_f32_16x16x32_bf16 v[48:51], v[174:177], v[182:185], v[48:51]
	v_mfma_f32_16x16x32_bf16 v[36:39], v[166:169], v[194:197], v[36:39]
	v_mfma_f32_16x16x32_bf16 v[32:35], v[174:177], v[194:197], v[32:35]
	v_mfma_f32_16x16x32_bf16 v[20:23], v[166:169], v[202:205], v[20:23]
	v_mfma_f32_16x16x32_bf16 v[16:19], v[174:177], v[202:205], v[16:19]
	v_mfma_f32_16x16x32_bf16 v[4:7], v[166:169], v[210:213], v[4:7]
	v_mfma_f32_16x16x32_bf16 v[0:3], v[174:177], v[210:213], v[0:3]
	v_mfma_f32_16x16x32_bf16 v[52:55], v[170:173], v[186:189], v[52:55]
	v_mfma_f32_16x16x32_bf16 v[48:51], v[178:181], v[186:189], v[48:51]
	v_mfma_f32_16x16x32_bf16 v[36:39], v[170:173], v[198:201], v[36:39]
	v_mfma_f32_16x16x32_bf16 v[32:35], v[178:181], v[198:201], v[32:35]
	v_mfma_f32_16x16x32_bf16 v[20:23], v[170:173], v[206:209], v[20:23]
	v_mfma_f32_16x16x32_bf16 v[16:19], v[178:181], v[206:209], v[16:19]
	v_mfma_f32_16x16x32_bf16 v[4:7], v[170:173], v[214:217], v[4:7]
	v_mfma_f32_16x16x32_bf16 v[0:3], v[178:181], v[214:217], v[0:3]
	s_setprio 0
	s_barrier
; #define PG8_STAGE(bufoff, gbase, voff) do { _Pragma("unroll") for (int _i = 0; _i < 2; ++_i) \
;         __builtin_amdgcn_global_load_lds((const unsigned*)((const char*)(gbase) + (voff)[_i]), (PG8_LAS unsigned*)(lds + (bufoff) + ldsw + _i * 8192), 16, 0, 0); } while (0)
; #define PG8_LDA(dst, b, h) do { _Pragma("unroll") for (int m = 0; m < 4; ++m) _Pragma("unroll") for (int k = 0; k < 2; ++k) dst[m][k] = *(const PG8_LAS bf16x8*)(lds + PG8_SA(b, h) + aoff + m * 2048 + k * 1024); } while (0)
; #define PG8_LDB(dst, b, h) do { _Pragma("unroll") for (int n = 0; n < 2; ++n) _Pragma("unroll") for (int k = 0; k < 2; ++k) dst[n][k] = *(const PG8_LAS bf16x8*)(lds + PG8_SB(b, h) + boff + n * 2048 + k * 1024); } while (0)
; #define PG8_MMA(ai, bj, At, Bt) do { __builtin_amdgcn_s_setprio(1); _Pragma("unroll") for (int m = 0; m < 4; ++m) _Pragma("unroll") for (int n = 0; n < 2; ++n) _Pragma("unroll") for (int k = 0; k < 2; ++k) \
;         acc[ai][bj][m][n] = __builtin_amdgcn_mfma_f32_16x16x32_bf16(Bt[n][k], At[m][k], acc[ai][bj][m][n], 0, 0, 0); __builtin_amdgcn_s_setprio(0); } while (0)
; #define PG8_WAIT_V(n) asm volatile("s_waitcnt vmcnt(" #n ")" ::: "memory")
; #define PG8_WAIT_L(n) asm volatile("s_waitcnt lgkmcnt(" #n ")" ::: "memory")
; #define PG8_BAR __builtin_amdgcn_s_barrier()
; #define PG8_SCHED __builtin_amdgcn_sched_barrier(0)
; template <class Epi, class Sched, bool ALIGN_EPI = false, bool SP2 = false>
; __device__ __forceinline__ void gemm_phase(PG8_LAS unsigned char* lds, const Gemm g, const Sched& S, const Epi& E) {
;     ...
;             PG8_LDB(B0, 1, 0); PG8_LDB(B1, 1, 1); PG8_SCHED; PG8_LDA(At, 1, 0); PG8_STAGE(PG8_SA(0, 1), a2 + hstep, voffA);
;             PG8_WAIT_V(8); PG8_WAIT_L(0); PG8_BAR; PG8_MMA(0, 0, At, B0); PG8_MMA(0, 1, At, B1); PG8_BAR; PG8_SCHED;
;             PG8_LDA(At, 1, 1); PG8_STAGE(PG8_SB(1, 0), b3, voffB); PG8_STAGE(PG8_SB(1, 1), b3 + hstep, voffB); PG8_STAGE(PG8_SA(1, 0), a3, voffA);
;             PG8_WAIT_V(8); PG8_WAIT_L(0); PG8_BAR; PG8_MMA(1, 0, At, B0); PG8_MMA(1, 1, At, B1); PG8_BAR; PG8_SCHED;
	s_add_i32 s65, 0, 0x18000
	s_add_i32 s66, 0, 0x1c000
	v_add_u32_e32 v162, s65, v149
	v_add_u32_e32 v178, s66, v149
	ds_read_b128 v[144:147], v162
	ds_read_b128 v[154:157], v162 offset:1024
	ds_read_b128 v[158:161], v162 offset:2048
	ds_read_b128 v[162:165], v162 offset:3072
	ds_read_b128 v[166:169], v178
	ds_read_b128 v[170:173], v178 offset:1024
	ds_read_b128 v[174:177], v178 offset:2048
	ds_read_b128 v[178:181], v178 offset:3072
	s_add_u32 s40, s40, 0x40000
	s_addc_u32 s41, s41, 0
	s_mov_b32 m0, s38
	ds_read_b128 v[182:185], v153 offset:32768
	ds_read_b128 v[186:189], v153 offset:33792
	ds_read_b128 v[194:197], v153 offset:34816
	ds_read_b128 v[198:201], v153 offset:35840
	ds_read_b128 v[202:205], v153 offset:36864
	ds_read_b128 v[206:209], v153 offset:37888
	ds_read_b128 v[210:213], v153 offset:38912
	global_load_lds_dwordx4 v128, s[40:41]
	s_mov_b32 m0, s39
	ds_read_b128 v[214:217], v153 offset:39936
	global_load_lds_dwordx4 v132, s[40:41]
	s_waitcnt vmcnt(8)
	s_waitcnt lgkmcnt(0)
	s_barrier
	s_setprio 1
	s_waitcnt lgkmcnt(0)
	v_mfma_f32_16x16x32_bf16 v[124:127], v[144:147], v[182:185], v[124:127]
	v_mfma_f32_16x16x32_bf16 v[120:123], v[158:161], v[182:185], v[120:123]
	v_mfma_f32_16x16x32_bf16 v[108:111], v[144:147], v[194:197], v[108:111]
	v_mfma_f32_16x16x32_bf16 v[104:107], v[158:161], v[194:197], v[104:107]
	v_mfma_f32_16x16x32_bf16 v[92:95], v[144:147], v[202:205], v[92:95]
	v_mfma_f32_16x16x32_bf16 v[88:91], v[158:161], v[202:205], v[88:91]
	v_mfma_f32_16x16x32_bf16 v[76:79], v[144:147], v[210:213], v[76:79]
	v_mfma_f32_16x16x32_bf16 v[72:75], v[158:161], v[210:213], v[72:75]
	v_mfma_f32_16x16x32_bf16 v[124:127], v[154:157], v[186:189], v[124:127]
	v_mfma_f32_16x16x32_bf16 v[120:123], v[162:165], v[186:189], v[120:123]
	v_mfma_f32_16x16x32_bf16 v[108:111], v[154:157], v[198:201], v[108:111]
	v_mfma_f32_16x16x32_bf16 v[104:107], v[162:165], v[198:201], v[104:107]
	v_mfma_f32_16x16x32_bf16 v[92:95], v[154:157], v[206:209], v[92:95]
	v_mfma_f32_16x16x32_bf16 v[88:91], v[162:165], v[206:209], v[88:91]
	v_mfma_f32_16x16x32_bf16 v[76:79], v[154:157], v[214:217], v[76:79]
	v_mfma_f32_16x16x32_bf16 v[72:75], v[162:165], v[214:217], v[72:75]
	s_setprio 0
	s_setprio 1
	v_mfma_f32_16x16x32_bf16 v[116:119], v[166:169], v[182:185], v[116:119]
	v_mfma_f32_16x16x32_bf16 v[112:115], v[174:177], v[182:185], v[112:115]
	v_mfma_f32_16x16x32_bf16 v[100:103], v[166:169], v[194:197], v[100:103]
	v_mfma_f32_16x16x32_bf16 v[96:99], v[174:177], v[194:197], v[96:99]
	v_mfma_f32_16x16x32_bf16 v[84:87], v[166:169], v[202:205], v[84:87]
	v_mfma_f32_16x16x32_bf16 v[80:83], v[174:177], v[202:205], v[80:83]
	v_mfma_f32_16x16x32_bf16 v[68:71], v[166:169], v[210:213], v[68:71]
	v_mfma_f32_16x16x32_bf16 v[64:67], v[174:177], v[210:213], v[64:67]
	v_mfma_f32_16x16x32_bf16 v[116:119], v[170:173], v[186:189], v[116:119]
	v_mfma_f32_16x16x32_bf16 v[112:115], v[178:181], v[186:189], v[112:115]
	v_mfma_f32_16x16x32_bf16 v[100:103], v[170:173], v[198:201], v[100:103]
	v_mfma_f32_16x16x32_bf16 v[96:99], v[178:181], v[198:201], v[96:99]
	v_mfma_f32_16x16x32_bf16 v[84:87], v[170:173], v[206:209], v[84:87]
	v_mfma_f32_16x16x32_bf16 v[80:83], v[178:181], v[206:209], v[80:83]
	v_mfma_f32_16x16x32_bf16 v[68:71], v[170:173], v[214:217], v[68:71]
	v_mfma_f32_16x16x32_bf16 v[64:67], v[178:181], v[214:217], v[64:67]
	s_setprio 0
	s_barrier
	s_add_i32 s40, s65, s0
	s_mov_b32 m0, s40
	ds_read_b128 v[182:185], v153 offset:49152
	ds_read_b128 v[186:189], v153 offset:50176
	ds_read_b128 v[194:197], v153 offset:51200
	ds_read_b128 v[198:201], v153 offset:52224
	global_load_lds_dwordx4 v130, vcc
	s_add_i32 m0, s40, 0x2000
	s_add_u32 s36, s36, 0x40080
	s_addc_u32 s37, s37, 0
	s_add_i32 s40, s66, s0
	global_load_lds_dwordx4 v134, vcc
	s_mov_b32 m0, s40
	ds_read_b128 v[214:217], v153 offset:56320
	global_load_lds_dwordx4 v130, s[36:37]
	s_add_i32 m0, s40, 0x2000
	ds_read_b128 v[210:213], v153 offset:55296
	global_load_lds_dwordx4 v134, s[36:37]
	s_mov_b32 m0, s44
	ds_read_b128 v[206:209], v153 offset:54272
	global_load_lds_dwordx4 v128, s[100:101]
	s_mov_b32 m0, s45
	ds_read_b128 v[202:205], v153 offset:53248
	global_load_lds_dwordx4 v132, s[100:101]
	s_waitcnt vmcnt(8)
	s_waitcnt lgkmcnt(0)
	s_barrier
	s_setprio 1
	s_waitcnt lgkmcnt(0)
	v_mfma_f32_16x16x32_bf16 v[60:63], v[144:147], v[182:185], v[60:63]
	v_mfma_f32_16x16x32_bf16 v[56:59], v[158:161], v[182:185], v[56:59]
	v_mfma_f32_16x16x32_bf16 v[44:47], v[144:147], v[194:197], v[44:47]
	v_mfma_f32_16x16x32_bf16 v[40:43], v[158:161], v[194:197], v[40:43]
	v_mfma_f32_16x16x32_bf16 v[28:31], v[144:147], v[202:205], v[28:31]
	v_mfma_f32_16x16x32_bf16 v[24:27], v[158:161], v[202:205], v[24:27]
	v_mfma_f32_16x16x32_bf16 v[12:15], v[144:147], v[210:213], v[12:15]
	v_mfma_f32_16x16x32_bf16 v[8:11], v[158:161], v[210:213], v[8:11]
	v_mfma_f32_16x16x32_bf16 v[60:63], v[154:157], v[186:189], v[60:63]
	v_mfma_f32_16x16x32_bf16 v[56:59], v[162:165], v[186:189], v[56:59]
	v_mfma_f32_16x16x32_bf16 v[44:47], v[154:157], v[198:201], v[44:47]
	v_mfma_f32_16x16x32_bf16 v[40:43], v[162:165], v[198:201], v[40:43]
	v_mfma_f32_16x16x32_bf16 v[28:31], v[154:157], v[206:209], v[28:31]
	v_mfma_f32_16x16x32_bf16 v[24:27], v[162:165], v[206:209], v[24:27]
	v_mfma_f32_16x16x32_bf16 v[12:15], v[154:157], v[214:217], v[12:15]
	v_mfma_f32_16x16x32_bf16 v[8:11], v[162:165], v[214:217], v[8:11]
	s_setprio 0
	s_setprio 1
	v_mfma_f32_16x16x32_bf16 v[52:55], v[166:169], v[182:185], v[52:55]
	v_mfma_f32_16x16x32_bf16 v[48:51], v[174:177], v[182:185], v[48:51]
	v_mfma_f32_16x16x32_bf16 v[36:39], v[166:169], v[194:197], v[36:39]
	v_mfma_f32_16x16x32_bf16 v[32:35], v[174:177], v[194:197], v[32:35]
	v_mfma_f32_16x16x32_bf16 v[20:23], v[166:169], v[202:205], v[20:23]
	v_mfma_f32_16x16x32_bf16 v[16:19], v[174:177], v[202:205], v[16:19]
	v_mfma_f32_16x16x32_bf16 v[4:7], v[166:169], v[210:213], v[4:7]
	v_mfma_f32_16x16x32_bf16 v[0:3], v[174:177], v[210:213], v[0:3]
	v_mfma_f32_16x16x32_bf16 v[52:55], v[170:173], v[186:189], v[52:55]
	v_mfma_f32_16x16x32_bf16 v[48:51], v[178:181], v[186:189], v[48:51]
	v_mfma_f32_16x16x32_bf16 v[36:39], v[170:173], v[198:201], v[36:39]
	v_mfma_f32_16x16x32_bf16 v[32:35], v[178:181], v[198:201], v[32:35]
	v_mfma_f32_16x16x32_bf16 v[20:23], v[170:173], v[206:209], v[20:23]
	v_mfma_f32_16x16x32_bf16 v[16:19], v[178:181], v[206:209], v[16:19]
	v_mfma_f32_16x16x32_bf16 v[4:7], v[170:173], v[214:217], v[4:7]
	v_mfma_f32_16x16x32_bf16 v[0:3], v[178:181], v[214:217], v[0:3]
	s_setprio 0
	s_barrier
	s_add_i32 s64, s64, 2
	s_add_u32 s34, s34, 0x100
	s_addc_u32 s35, s35, 0
	s_add_u32 s62, s62, 0x100
	s_addc_u32 s63, s63, 0
	s_cmp_gt_u32 s64, 13
	s_cbranch_scc0 .LBB0_413
	s_and_b64 vcc, exec, s[18:19]
	s_cbranch_vccz .LBB0_416
	s_barrier

; #define PG8_STAGE(bufoff, gbase, voff) do { _Pragma("unroll") for (int _i = 0; _i < 2; ++_i) \
;         __builtin_amdgcn_global_load_lds((const unsigned*)((const char*)(gbase) + (voff)[_i]), (PG8_LAS unsigned*)(lds + (bufoff) + ldsw + _i * 8192), 16, 0, 0); } while (0)
; #define PG8_LDA(dst, b, h) do { _Pragma("unroll") for (int m = 0; m < 4; ++m) _Pragma("unroll") for (int k = 0; k < 2; ++k) dst[m][k] = *(const PG8_LAS bf16x8*)(lds + PG8_SA(b, h) + aoff + m * 2048 + k * 1024); } while (0)
; #define PG8_LDB(dst, b, h) do { _Pragma("unroll") for (int n = 0; n < 2; ++n) _Pragma("unroll") for (int k = 0; k < 2; ++k) dst[n][k] = *(const PG8_LAS bf16x8*)(lds + PG8_SB(b, h) + boff + n * 2048 + k * 1024); } while (0)
; #define PG8_MMA(ai, bj, At, Bt) do { __builtin_amdgcn_s_setprio(1); _Pragma("unroll") for (int m = 0; m < 4; ++m) _Pragma("unroll") for (int n = 0; n < 2; ++n) _Pragma("unroll") for (int k = 0; k < 2; ++k) \
;         acc[ai][bj][m][n] = __builtin_amdgcn_mfma_f32_16x16x32_bf16(Bt[n][k], At[m][k], acc[ai][bj][m][n], 0, 0, 0); __builtin_amdgcn_s_setprio(0); } while (0)
; #define PG8_WAIT_V(n) asm volatile("s_waitcnt vmcnt(" #n ")" ::: "memory")
; #define PG8_WAIT_L(n) asm volatile("s_waitcnt lgkmcnt(" #n ")" ::: "memory")
; #define PG8_BAR __builtin_amdgcn_s_barrier()
; #define PG8_SCHED __builtin_amdgcn_sched_barrier(0)
; template <class Epi, class Sched, bool ALIGN_EPI = false, bool SP2 = false>
; __device__ __forceinline__ void gemm_phase(PG8_LAS unsigned char* lds, const Gemm g, const Sched& S, const Epi& E) {
;     ...
;             PG8_LDB(B0, 0, 0); PG8_LDB(B1, 0, 1); PG8_SCHED; PG8_LDA(At, 0, 0); PG8_STAGE(PG8_SA(1, 1), a1 + hstep, voffA);
;             PG8_WAIT_V(8); PG8_WAIT_L(0); PG8_BAR; PG8_MMA(0, 0, At, B0); PG8_MMA(0, 1, At, B1); PG8_BAR; PG8_SCHED;
;             PG8_LDA(At, 0, 1); PG8_STAGE(PG8_SB(0, 0), b2, voffB); PG8_STAGE(PG8_SB(0, 1), b2 + hstep, voffB); PG8_STAGE(PG8_SA(0, 0), a2, voffA);
;             PG8_WAIT_V(8); PG8_WAIT_L(0); PG8_BAR; PG8_MMA(1, 0, At, B0); PG8_MMA(1, 1, At, B1); PG8_BAR; PG8_SCHED;
.LBB0_462:
	ds_read_b128 v[156:159], v151
	ds_read_b128 v[160:163], v151 offset:1024
	ds_read_b128 v[164:167], v151 offset:2048
	ds_read_b128 v[168:171], v151 offset:3072
	ds_read_b128 v[172:175], v152
	ds_read_b128 v[176:179], v152 offset:1024
	ds_read_b128 v[180:183], v152 offset:2048
	ds_read_b128 v[184:187], v152 offset:3072
	s_add_u32 s26, s24, 0xfffc0080
	s_addc_u32 s27, s25, -1
	s_cmp_eq_u32 s50, 12
	s_cselect_b32 s29, s17, s27
	s_cselect_b32 s28, s41, s26
	s_cselect_b32 s27, s11, s45
	s_cselect_b32 s26, s42, s44
	s_add_u32 vcc_lo, s26, 0x80
	s_addc_u32 vcc_hi, s27, 0
	s_add_u32 s100, s28, 0x80
	s_addc_u32 s101, s29, 0
	s_add_i32 m0, s1, 0xc000
	ds_read_b128 v[194:197], v153
	ds_read_b128 v[198:201], v153 offset:1024
	ds_read_b128 v[202:205], v153 offset:2048
	ds_read_b128 v[206:209], v153 offset:3072
	ds_read_b128 v[210:213], v153 offset:4096
	ds_read_b128 v[214:217], v153 offset:5120
	ds_read_b128 v[218:221], v153 offset:6144
	global_load_lds_dwordx4 v138, s[24:25]
	s_add_i32 m0, s1, 0xe000
	ds_read_b128 v[222:225], v153 offset:7168
	global_load_lds_dwordx4 v140, s[24:25]
	s_waitcnt vmcnt(8)
	s_waitcnt lgkmcnt(0)
	s_barrier
	s_setprio 1
	s_waitcnt lgkmcnt(0)
	v_mfma_f32_16x16x32_bf16 v[124:127], v[156:159], v[194:197], v[124:127]
	v_mfma_f32_16x16x32_bf16 v[120:123], v[164:167], v[194:197], v[120:123]
	v_mfma_f32_16x16x32_bf16 v[108:111], v[156:159], v[202:205], v[108:111]
	v_mfma_f32_16x16x32_bf16 v[104:107], v[164:167], v[202:205], v[104:107]
	v_mfma_f32_16x16x32_bf16 v[92:95], v[156:159], v[210:213], v[92:95]
	v_mfma_f32_16x16x32_bf16 v[88:91], v[164:167], v[210:213], v[88:91]
	v_mfma_f32_16x16x32_bf16 v[76:79], v[156:159], v[218:221], v[76:79]
	v_mfma_f32_16x16x32_bf16 v[72:75], v[164:167], v[218:221], v[72:75]
	v_mfma_f32_16x16x32_bf16 v[124:127], v[160:163], v[198:201], v[124:127]
	v_mfma_f32_16x16x32_bf16 v[120:123], v[168:171], v[198:201], v[120:123]
	v_mfma_f32_16x16x32_bf16 v[108:111], v[160:163], v[206:209], v[108:111]
	v_mfma_f32_16x16x32_bf16 v[104:107], v[168:171], v[206:209], v[104:107]
	v_mfma_f32_16x16x32_bf16 v[92:95], v[160:163], v[214:217], v[92:95]
	v_mfma_f32_16x16x32_bf16 v[88:91], v[168:171], v[214:217], v[88:91]
	v_mfma_f32_16x16x32_bf16 v[76:79], v[160:163], v[222:225], v[76:79]
	v_mfma_f32_16x16x32_bf16 v[72:75], v[168:171], v[222:225], v[72:75]
	s_setprio 0
	s_setprio 1
	v_mfma_f32_16x16x32_bf16 v[116:119], v[172:175], v[194:197], v[116:119]
	v_mfma_f32_16x16x32_bf16 v[112:115], v[180:183], v[194:197], v[112:115]
	v_mfma_f32_16x16x32_bf16 v[100:103], v[172:175], v[202:205], v[100:103]
	v_mfma_f32_16x16x32_bf16 v[96:99], v[180:183], v[202:205], v[96:99]
	v_mfma_f32_16x16x32_bf16 v[84:87], v[172:175], v[210:213], v[84:87]
	v_mfma_f32_16x16x32_bf16 v[80:83], v[180:183], v[210:213], v[80:83]
	v_mfma_f32_16x16x32_bf16 v[68:71], v[172:175], v[218:221], v[68:71]
	v_mfma_f32_16x16x32_bf16 v[64:67], v[180:183], v[218:221], v[64:67]
	v_mfma_f32_16x16x32_bf16 v[116:119], v[176:179], v[198:201], v[116:119]
	v_mfma_f32_16x16x32_bf16 v[112:115], v[184:187], v[198:201], v[112:115]
	v_mfma_f32_16x16x32_bf16 v[100:103], v[176:179], v[206:209], v[100:103]
	v_mfma_f32_16x16x32_bf16 v[96:99], v[184:187], v[206:209], v[96:99]
	v_mfma_f32_16x16x32_bf16 v[84:87], v[176:179], v[214:217], v[84:87]
	v_mfma_f32_16x16x32_bf16 v[80:83], v[184:187], v[214:217], v[80:83]
	v_mfma_f32_16x16x32_bf16 v[68:71], v[176:179], v[222:225], v[68:71]
	v_mfma_f32_16x16x32_bf16 v[64:67], v[184:187], v[222:225], v[64:67]
	s_setprio 0
	s_barrier
	s_add_i32 s51, s38, s0
	s_mov_b32 m0, s51
	ds_read_b128 v[194:197], v153 offset:16384
	ds_read_b128 v[198:201], v153 offset:17408
	ds_read_b128 v[202:205], v153 offset:18432
	ds_read_b128 v[206:209], v153 offset:19456
	global_load_lds_dwordx4 v132, s[26:27]
	s_add_i32 m0, s51, 0x2000
	s_add_u32 s56, s26, 0x40000
	s_addc_u32 s57, s27, 0
	s_add_i32 s51, s39, s0
	global_load_lds_dwordx4 v128, s[26:27]
	s_mov_b32 m0, s51
	ds_read_b128 v[222:225], v153 offset:23552
	global_load_lds_dwordx4 v132, s[56:57]
	s_add_i32 m0, s51, 0x2000
	ds_read_b128 v[218:221], v153 offset:22528
	global_load_lds_dwordx4 v128, s[56:57]
	s_mov_b32 m0, s1
	ds_read_b128 v[214:217], v153 offset:21504
	global_load_lds_dwordx4 v134, s[28:29]
	s_mov_b32 m0, s23
	ds_read_b128 v[210:213], v153 offset:20480
	global_load_lds_dwordx4 v130, s[28:29]
	s_waitcnt vmcnt(8)
	s_waitcnt lgkmcnt(0)
	s_barrier
	s_setprio 1
	s_waitcnt lgkmcnt(0)
	v_mfma_f32_16x16x32_bf16 v[60:63], v[156:159], v[194:197], v[60:63]
	v_mfma_f32_16x16x32_bf16 v[56:59], v[164:167], v[194:197], v[56:59]
	v_mfma_f32_16x16x32_bf16 v[44:47], v[156:159], v[202:205], v[44:47]
	v_mfma_f32_16x16x32_bf16 v[40:43], v[164:167], v[202:205], v[40:43]
	v_mfma_f32_16x16x32_bf16 v[28:31], v[156:159], v[210:213], v[28:31]
	v_mfma_f32_16x16x32_bf16 v[24:27], v[164:167], v[210:213], v[24:27]
	v_mfma_f32_16x16x32_bf16 v[12:15], v[156:159], v[218:221], v[12:15]
	v_mfma_f32_16x16x32_bf16 v[8:11], v[164:167], v[218:221], v[8:11]
	v_mfma_f32_16x16x32_bf16 v[60:63], v[160:163], v[198:201], v[60:63]
	v_mfma_f32_16x16x32_bf16 v[56:59], v[168:171], v[198:201], v[56:59]
	v_mfma_f32_16x16x32_bf16 v[44:47], v[160:163], v[206:209], v[44:47]
	v_mfma_f32_16x16x32_bf16 v[40:43], v[168:171], v[206:209], v[40:43]
	v_mfma_f32_16x16x32_bf16 v[28:31], v[160:163], v[214:217], v[28:31]
	v_mfma_f32_16x16x32_bf16 v[24:27], v[168:171], v[214:217], v[24:27]
	v_mfma_f32_16x16x32_bf16 v[12:15], v[160:163], v[222:225], v[12:15]
	v_mfma_f32_16x16x32_bf16 v[8:11], v[168:171], v[222:225], v[8:11]
	s_setprio 0
	s_setprio 1
	v_mfma_f32_16x16x32_bf16 v[52:55], v[172:175], v[194:197], v[52:55]
	v_mfma_f32_16x16x32_bf16 v[48:51], v[180:183], v[194:197], v[48:51]
	v_mfma_f32_16x16x32_bf16 v[36:39], v[172:175], v[202:205], v[36:39]
	v_mfma_f32_16x16x32_bf16 v[32:35], v[180:183], v[202:205], v[32:35]
	v_mfma_f32_16x16x32_bf16 v[20:23], v[172:175], v[210:213], v[20:23]
	v_mfma_f32_16x16x32_bf16 v[16:19], v[180:183], v[210:213], v[16:19]
	v_mfma_f32_16x16x32_bf16 v[4:7], v[172:175], v[218:221], v[4:7]
	v_mfma_f32_16x16x32_bf16 v[0:3], v[180:183], v[218:221], v[0:3]
	v_mfma_f32_16x16x32_bf16 v[52:55], v[176:179], v[198:201], v[52:55]
	v_mfma_f32_16x16x32_bf16 v[48:51], v[184:187], v[198:201], v[48:51]
	v_mfma_f32_16x16x32_bf16 v[36:39], v[176:179], v[206:209], v[36:39]
	v_mfma_f32_16x16x32_bf16 v[32:35], v[184:187], v[206:209], v[32:35]
	v_mfma_f32_16x16x32_bf16 v[20:23], v[176:179], v[214:217], v[20:23]
	v_mfma_f32_16x16x32_bf16 v[16:19], v[184:187], v[214:217], v[16:19]
	v_mfma_f32_16x16x32_bf16 v[4:7], v[176:179], v[222:225], v[4:7]
	v_mfma_f32_16x16x32_bf16 v[0:3], v[184:187], v[222:225], v[0:3]
	s_setprio 0
	s_barrier
; #define PG8_STAGE(bufoff, gbase, voff) do { _Pragma("unroll") for (int _i = 0; _i < 2; ++_i) \
;         __builtin_amdgcn_global_load_lds((const unsigned*)((const char*)(gbase) + (voff)[_i]), (PG8_LAS unsigned*)(lds + (bufoff) + ldsw + _i * 8192), 16, 0, 0); } while (0)
; #define PG8_LDA(dst, b, h) do { _Pragma("unroll") for (int m = 0; m < 4; ++m) _Pragma("unroll") for (int k = 0; k < 2; ++k) dst[m][k] = *(const PG8_LAS bf16x8*)(lds + PG8_SA(b, h) + aoff + m * 2048 + k * 1024); } while (0)
; #define PG8_LDB(dst, b, h) do { _Pragma("unroll") for (int n = 0; n < 2; ++n) _Pragma("unroll") for (int k = 0; k < 2; ++k) dst[n][k] = *(const PG8_LAS bf16x8*)(lds + PG8_SB(b, h) + boff + n * 2048 + k * 1024); } while (0)
; #define PG8_MMA(ai, bj, At, Bt) do { __builtin_amdgcn_s_setprio(1); _Pragma("unroll") for (int m = 0; m < 4; ++m) _Pragma("unroll") for (int n = 0; n < 2; ++n) _Pragma("unroll") for (int k = 0; k < 2; ++k) \
;         acc[ai][bj][m][n] = __builtin_amdgcn_mfma_f32_16x16x32_bf16(Bt[n][k], At[m][k], acc[ai][bj][m][n], 0, 0, 0); __builtin_amdgcn_s_setprio(0); } while (0)
; #define PG8_WAIT_V(n) asm volatile("s_waitcnt vmcnt(" #n ")" ::: "memory")
; #define PG8_WAIT_L(n) asm volatile("s_waitcnt lgkmcnt(" #n ")" ::: "memory")
; #define PG8_BAR __builtin_amdgcn_s_barrier()
; #define PG8_SCHED __builtin_amdgcn_sched_barrier(0)
; template <class Epi, class Sched, bool ALIGN_EPI = false, bool SP2 = false>
; __device__ __forceinline__ void gemm_phase(PG8_LAS unsigned char* lds, const Gemm g, const Sched& S, const Epi& E) {
;     ...
;             PG8_LDB(B0, 1, 0); PG8_LDB(B1, 1, 1); PG8_SCHED; PG8_LDA(At, 1, 0); PG8_STAGE(PG8_SA(0, 1), a2 + hstep, voffA);
;             PG8_WAIT_V(8); PG8_WAIT_L(0); PG8_BAR; PG8_MMA(0, 0, At, B0); PG8_MMA(0, 1, At, B1); PG8_BAR; PG8_SCHED;
;             PG8_LDA(At, 1, 1); PG8_STAGE(PG8_SB(1, 0), b3, voffB); PG8_STAGE(PG8_SB(1, 1), b3 + hstep, voffB); PG8_STAGE(PG8_SA(1, 0), a3, voffA);
;             PG8_WAIT_V(8); PG8_WAIT_L(0); PG8_BAR; PG8_MMA(1, 0, At, B0); PG8_MMA(1, 1, At, B1); PG8_BAR; PG8_SCHED;
	s_add_i32 s51, 0, 0x18000
	v_add_u32_e32 v155, s51, v149
	s_add_i32 s56, 0, 0x1c000
	ds_read_b128 v[156:159], v155
	ds_read_b128 v[160:163], v155 offset:1024
	ds_read_b128 v[164:167], v155 offset:2048
	ds_read_b128 v[168:171], v155 offset:3072
	v_add_u32_e32 v155, s56, v149
	ds_read_b128 v[172:175], v155
	ds_read_b128 v[176:179], v155 offset:1024
	ds_read_b128 v[180:183], v155 offset:2048
	ds_read_b128 v[184:187], v155 offset:3072
	s_add_u32 s28, s28, 0x40000
	s_addc_u32 s29, s29, 0
	s_mov_b32 m0, s31
	ds_read_b128 v[194:197], v153 offset:32768
	ds_read_b128 v[198:201], v153 offset:33792
	ds_read_b128 v[202:205], v153 offset:34816
	ds_read_b128 v[206:209], v153 offset:35840
	ds_read_b128 v[210:213], v153 offset:36864
	ds_read_b128 v[214:217], v153 offset:37888
	ds_read_b128 v[218:221], v153 offset:38912
	global_load_lds_dwordx4 v134, s[28:29]
	s_mov_b32 m0, s34
	ds_read_b128 v[222:225], v153 offset:39936
	global_load_lds_dwordx4 v130, s[28:29]
	s_waitcnt vmcnt(8)
	s_waitcnt lgkmcnt(0)
	s_barrier
	s_setprio 1
	s_waitcnt lgkmcnt(0)
	v_mfma_f32_16x16x32_bf16 v[124:127], v[156:159], v[194:197], v[124:127]
	v_mfma_f32_16x16x32_bf16 v[120:123], v[164:167], v[194:197], v[120:123]
	v_mfma_f32_16x16x32_bf16 v[108:111], v[156:159], v[202:205], v[108:111]
	v_mfma_f32_16x16x32_bf16 v[104:107], v[164:167], v[202:205], v[104:107]
	v_mfma_f32_16x16x32_bf16 v[92:95], v[156:159], v[210:213], v[92:95]
	v_mfma_f32_16x16x32_bf16 v[88:91], v[164:167], v[210:213], v[88:91]
	v_mfma_f32_16x16x32_bf16 v[76:79], v[156:159], v[218:221], v[76:79]
	v_mfma_f32_16x16x32_bf16 v[72:75], v[164:167], v[218:221], v[72:75]
	v_mfma_f32_16x16x32_bf16 v[124:127], v[160:163], v[198:201], v[124:127]
	v_mfma_f32_16x16x32_bf16 v[120:123], v[168:171], v[198:201], v[120:123]
	v_mfma_f32_16x16x32_bf16 v[108:111], v[160:163], v[206:209], v[108:111]
	v_mfma_f32_16x16x32_bf16 v[104:107], v[168:171], v[206:209], v[104:107]
	v_mfma_f32_16x16x32_bf16 v[92:95], v[160:163], v[214:217], v[92:95]
	v_mfma_f32_16x16x32_bf16 v[88:91], v[168:171], v[214:217], v[88:91]
	v_mfma_f32_16x16x32_bf16 v[76:79], v[160:163], v[222:225], v[76:79]
	v_mfma_f32_16x16x32_bf16 v[72:75], v[168:171], v[222:225], v[72:75]
	s_setprio 0
	s_setprio 1
	v_mfma_f32_16x16x32_bf16 v[116:119], v[172:175], v[194:197], v[116:119]
	v_mfma_f32_16x16x32_bf16 v[112:115], v[180:183], v[194:197], v[112:115]
	v_mfma_f32_16x16x32_bf16 v[100:103], v[172:175], v[202:205], v[100:103]
	v_mfma_f32_16x16x32_bf16 v[96:99], v[180:183], v[202:205], v[96:99]
	v_mfma_f32_16x16x32_bf16 v[84:87], v[172:175], v[210:213], v[84:87]
	v_mfma_f32_16x16x32_bf16 v[80:83], v[180:183], v[210:213], v[80:83]
	v_mfma_f32_16x16x32_bf16 v[68:71], v[172:175], v[218:221], v[68:71]
	v_mfma_f32_16x16x32_bf16 v[64:67], v[180:183], v[218:221], v[64:67]
	v_mfma_f32_16x16x32_bf16 v[116:119], v[176:179], v[198:201], v[116:119]
	v_mfma_f32_16x16x32_bf16 v[112:115], v[184:187], v[198:201], v[112:115]
	v_mfma_f32_16x16x32_bf16 v[100:103], v[176:179], v[206:209], v[100:103]
	v_mfma_f32_16x16x32_bf16 v[96:99], v[184:187], v[206:209], v[96:99]
	v_mfma_f32_16x16x32_bf16 v[84:87], v[176:179], v[214:217], v[84:87]
	v_mfma_f32_16x16x32_bf16 v[80:83], v[184:187], v[214:217], v[80:83]
	v_mfma_f32_16x16x32_bf16 v[68:71], v[176:179], v[222:225], v[68:71]
	v_mfma_f32_16x16x32_bf16 v[64:67], v[184:187], v[222:225], v[64:67]
	s_setprio 0
	s_barrier
	s_add_i32 s28, s51, s0
	s_mov_b32 m0, s28
	ds_read_b128 v[194:197], v153 offset:49152
	ds_read_b128 v[198:201], v153 offset:50176
	ds_read_b128 v[202:205], v153 offset:51200
	ds_read_b128 v[206:209], v153 offset:52224
	global_load_lds_dwordx4 v132, vcc
	s_add_i32 m0, s28, 0x2000
	s_add_u32 s26, s26, 0x40080
	s_addc_u32 s27, s27, 0
	s_add_i32 s28, s56, s0
	global_load_lds_dwordx4 v128, vcc
	s_mov_b32 m0, s28
	ds_read_b128 v[222:225], v153 offset:56320
	global_load_lds_dwordx4 v132, s[26:27]
	s_add_i32 m0, s28, 0x2000
	ds_read_b128 v[218:221], v153 offset:55296
	global_load_lds_dwordx4 v128, s[26:27]
	s_mov_b32 m0, s36
	ds_read_b128 v[214:217], v153 offset:54272
	global_load_lds_dwordx4 v134, s[100:101]
	s_mov_b32 m0, s37
	ds_read_b128 v[210:213], v153 offset:53248
	global_load_lds_dwordx4 v130, s[100:101]
	s_waitcnt vmcnt(8)
	s_waitcnt lgkmcnt(0)
	s_barrier
	s_setprio 1
	s_waitcnt lgkmcnt(0)
	v_mfma_f32_16x16x32_bf16 v[60:63], v[156:159], v[194:197], v[60:63]
	v_mfma_f32_16x16x32_bf16 v[56:59], v[164:167], v[194:197], v[56:59]
	v_mfma_f32_16x16x32_bf16 v[44:47], v[156:159], v[202:205], v[44:47]
	v_mfma_f32_16x16x32_bf16 v[40:43], v[164:167], v[202:205], v[40:43]
	v_mfma_f32_16x16x32_bf16 v[28:31], v[156:159], v[210:213], v[28:31]
	v_mfma_f32_16x16x32_bf16 v[24:27], v[164:167], v[210:213], v[24:27]
	v_mfma_f32_16x16x32_bf16 v[12:15], v[156:159], v[218:221], v[12:15]
	v_mfma_f32_16x16x32_bf16 v[8:11], v[164:167], v[218:221], v[8:11]
	v_mfma_f32_16x16x32_bf16 v[60:63], v[160:163], v[198:201], v[60:63]
	v_mfma_f32_16x16x32_bf16 v[56:59], v[168:171], v[198:201], v[56:59]
	v_mfma_f32_16x16x32_bf16 v[44:47], v[160:163], v[206:209], v[44:47]
	v_mfma_f32_16x16x32_bf16 v[40:43], v[168:171], v[206:209], v[40:43]
	v_mfma_f32_16x16x32_bf16 v[28:31], v[160:163], v[214:217], v[28:31]
	v_mfma_f32_16x16x32_bf16 v[24:27], v[168:171], v[214:217], v[24:27]
	v_mfma_f32_16x16x32_bf16 v[12:15], v[160:163], v[222:225], v[12:15]
	v_mfma_f32_16x16x32_bf16 v[8:11], v[168:171], v[222:225], v[8:11]
	s_setprio 0
	s_setprio 1
	v_mfma_f32_16x16x32_bf16 v[52:55], v[172:175], v[194:197], v[52:55]
	v_mfma_f32_16x16x32_bf16 v[48:51], v[180:183], v[194:197], v[48:51]
	v_mfma_f32_16x16x32_bf16 v[36:39], v[172:175], v[202:205], v[36:39]
	v_mfma_f32_16x16x32_bf16 v[32:35], v[180:183], v[202:205], v[32:35]
	v_mfma_f32_16x16x32_bf16 v[20:23], v[172:175], v[210:213], v[20:23]
	v_mfma_f32_16x16x32_bf16 v[16:19], v[180:183], v[210:213], v[16:19]
	v_mfma_f32_16x16x32_bf16 v[4:7], v[172:175], v[218:221], v[4:7]
	v_mfma_f32_16x16x32_bf16 v[0:3], v[180:183], v[218:221], v[0:3]
	v_mfma_f32_16x16x32_bf16 v[52:55], v[176:179], v[198:201], v[52:55]
	v_mfma_f32_16x16x32_bf16 v[48:51], v[184:187], v[198:201], v[48:51]
	v_mfma_f32_16x16x32_bf16 v[36:39], v[176:179], v[206:209], v[36:39]
	v_mfma_f32_16x16x32_bf16 v[32:35], v[184:187], v[206:209], v[32:35]
	v_mfma_f32_16x16x32_bf16 v[20:23], v[176:179], v[214:217], v[20:23]
	v_mfma_f32_16x16x32_bf16 v[16:19], v[184:187], v[214:217], v[16:19]
	v_mfma_f32_16x16x32_bf16 v[4:7], v[176:179], v[222:225], v[4:7]
	v_mfma_f32_16x16x32_bf16 v[0:3], v[184:187], v[222:225], v[0:3]
	s_setprio 0
	s_barrier
	s_add_i32 s50, s50, 2
	s_add_u32 s24, s24, 0x100
	s_addc_u32 s25, s25, 0
	s_add_u32 s44, s44, 0x100
	s_addc_u32 s45, s45, 0
	s_cmp_gt_u32 s50, 13
	s_cbranch_scc0 .LBB0_462
	s_and_b64 vcc, exec, s[14:15]
	s_cbranch_vccz .LBB0_465
	s_barrier

; #define PG8_STAGE(bufoff, gbase, voff) do { _Pragma("unroll") for (int _i = 0; _i < 2; ++_i) \
;         __builtin_amdgcn_global_load_lds((const unsigned*)((const char*)(gbase) + (voff)[_i]), (PG8_LAS unsigned*)(lds + (bufoff) + ldsw + _i * 8192), 16, 0, 0); } while (0)
; #define PG8_LDA(dst, b, h) do { _Pragma("unroll") for (int m = 0; m < 4; ++m) _Pragma("unroll") for (int k = 0; k < 2; ++k) dst[m][k] = *(const PG8_LAS bf16x8*)(lds + PG8_SA(b, h) + aoff + m * 2048 + k * 1024); } while (0)
; #define PG8_LDB(dst, b, h) do { _Pragma("unroll") for (int n = 0; n < 2; ++n) _Pragma("unroll") for (int k = 0; k < 2; ++k) dst[n][k] = *(const PG8_LAS bf16x8*)(lds + PG8_SB(b, h) + boff + n * 2048 + k * 1024); } while (0)
; #define PG8_MMA(ai, bj, At, Bt) do { __builtin_amdgcn_s_setprio(1); _Pragma("unroll") for (int m = 0; m < 4; ++m) _Pragma("unroll") for (int n = 0; n < 2; ++n) _Pragma("unroll") for (int k = 0; k < 2; ++k) \
;         acc[ai][bj][m][n] = __builtin_amdgcn_mfma_f32_16x16x32_bf16(Bt[n][k], At[m][k], acc[ai][bj][m][n], 0, 0, 0); __builtin_amdgcn_s_setprio(0); } while (0)
; #define PG8_WAIT_V(n) asm volatile("s_waitcnt vmcnt(" #n ")" ::: "memory")
; #define PG8_WAIT_L(n) asm volatile("s_waitcnt lgkmcnt(" #n ")" ::: "memory")
; #define PG8_BAR __builtin_amdgcn_s_barrier()
; #define PG8_SCHED __builtin_amdgcn_sched_barrier(0)
; template <class Epi, class Sched, bool ALIGN_EPI = false, bool SP2 = false>
; __device__ __forceinline__ void gemm_phase(PG8_LAS unsigned char* lds, const Gemm g, const Sched& S, const Epi& E) {
;     ...
;             PG8_LDB(B0, 0, 0); PG8_LDB(B1, 0, 1); PG8_SCHED; PG8_LDA(At, 0, 0); PG8_STAGE(PG8_SA(1, 1), a1 + hstep, voffA);
;             PG8_WAIT_V(8); PG8_WAIT_L(0); PG8_BAR; PG8_MMA(0, 0, At, B0); PG8_MMA(0, 1, At, B1); PG8_BAR; PG8_SCHED;
;             PG8_LDA(At, 0, 1); PG8_STAGE(PG8_SB(0, 0), b2, voffB); PG8_STAGE(PG8_SB(0, 1), b2 + hstep, voffB); PG8_STAGE(PG8_SA(0, 0), a2, voffA);
;             PG8_WAIT_V(8); PG8_WAIT_L(0); PG8_BAR; PG8_MMA(1, 0, At, B0); PG8_MMA(1, 1, At, B1); PG8_BAR; PG8_SCHED;
.LBB0_501:
	ds_read_b128 v[144:147], v151
	ds_read_b128 v[154:157], v151 offset:1024
	ds_read_b128 v[158:161], v151 offset:2048
	ds_read_b128 v[162:165], v151 offset:3072
	ds_read_b128 v[166:169], v152
	ds_read_b128 v[170:173], v152 offset:1024
	ds_read_b128 v[174:177], v152 offset:2048
	ds_read_b128 v[178:181], v152 offset:3072
	s_add_u32 s28, s26, 0xfff00080
	s_addc_u32 s29, s27, -1
	s_cmp_eq_u32 s56, 60
	s_cselect_b32 s35, s19, s29
	s_cselect_b32 s34, s25, s28
	s_cselect_b32 s29, s17, s51
	s_cselect_b32 s28, s45, s50
	s_add_u32 vcc_lo, s28, 0x80
	s_addc_u32 vcc_hi, s29, 0
	s_add_u32 s100, s34, 0x80
	s_addc_u32 s101, s35, 0
	s_add_i32 m0, s1, 0xc000
	ds_read_b128 v[182:185], v153
	ds_read_b128 v[186:189], v153 offset:1024
	ds_read_b128 v[194:197], v153 offset:2048
	ds_read_b128 v[198:201], v153 offset:3072
	ds_read_b128 v[202:205], v153 offset:4096
	ds_read_b128 v[206:209], v153 offset:5120
	ds_read_b128 v[210:213], v153 offset:6144
	global_load_lds_dwordx4 v136, s[26:27]
	s_add_i32 m0, s1, 0xe000
	ds_read_b128 v[214:217], v153 offset:7168
	global_load_lds_dwordx4 v138, s[26:27]
	s_waitcnt vmcnt(8)
	s_waitcnt lgkmcnt(0)
	s_barrier
	s_setprio 1
	s_waitcnt lgkmcnt(0)
	v_mfma_f32_16x16x32_bf16 v[124:127], v[144:147], v[182:185], v[124:127]
	v_mfma_f32_16x16x32_bf16 v[120:123], v[158:161], v[182:185], v[120:123]
	v_mfma_f32_16x16x32_bf16 v[108:111], v[144:147], v[194:197], v[108:111]
	v_mfma_f32_16x16x32_bf16 v[104:107], v[158:161], v[194:197], v[104:107]
	v_mfma_f32_16x16x32_bf16 v[92:95], v[144:147], v[202:205], v[92:95]
	v_mfma_f32_16x16x32_bf16 v[88:91], v[158:161], v[202:205], v[88:91]
	v_mfma_f32_16x16x32_bf16 v[76:79], v[144:147], v[210:213], v[76:79]
	v_mfma_f32_16x16x32_bf16 v[72:75], v[158:161], v[210:213], v[72:75]
	v_mfma_f32_16x16x32_bf16 v[124:127], v[154:157], v[186:189], v[124:127]
	v_mfma_f32_16x16x32_bf16 v[120:123], v[162:165], v[186:189], v[120:123]
	v_mfma_f32_16x16x32_bf16 v[108:111], v[154:157], v[198:201], v[108:111]
	v_mfma_f32_16x16x32_bf16 v[104:107], v[162:165], v[198:201], v[104:107]
	v_mfma_f32_16x16x32_bf16 v[92:95], v[154:157], v[206:209], v[92:95]
	v_mfma_f32_16x16x32_bf16 v[88:91], v[162:165], v[206:209], v[88:91]
	v_mfma_f32_16x16x32_bf16 v[76:79], v[154:157], v[214:217], v[76:79]
	v_mfma_f32_16x16x32_bf16 v[72:75], v[162:165], v[214:217], v[72:75]
	s_setprio 0
	s_setprio 1
	v_mfma_f32_16x16x32_bf16 v[116:119], v[166:169], v[182:185], v[116:119]
	v_mfma_f32_16x16x32_bf16 v[112:115], v[174:177], v[182:185], v[112:115]
	v_mfma_f32_16x16x32_bf16 v[100:103], v[166:169], v[194:197], v[100:103]
	v_mfma_f32_16x16x32_bf16 v[96:99], v[174:177], v[194:197], v[96:99]
	v_mfma_f32_16x16x32_bf16 v[84:87], v[166:169], v[202:205], v[84:87]
	v_mfma_f32_16x16x32_bf16 v[80:83], v[174:177], v[202:205], v[80:83]
	v_mfma_f32_16x16x32_bf16 v[68:71], v[166:169], v[210:213], v[68:71]
	v_mfma_f32_16x16x32_bf16 v[64:67], v[174:177], v[210:213], v[64:67]
	v_mfma_f32_16x16x32_bf16 v[116:119], v[170:173], v[186:189], v[116:119]
	v_mfma_f32_16x16x32_bf16 v[112:115], v[178:181], v[186:189], v[112:115]
	v_mfma_f32_16x16x32_bf16 v[100:103], v[170:173], v[198:201], v[100:103]
	v_mfma_f32_16x16x32_bf16 v[96:99], v[178:181], v[198:201], v[96:99]
	v_mfma_f32_16x16x32_bf16 v[84:87], v[170:173], v[206:209], v[84:87]
	v_mfma_f32_16x16x32_bf16 v[80:83], v[178:181], v[206:209], v[80:83]
	v_mfma_f32_16x16x32_bf16 v[68:71], v[170:173], v[214:217], v[68:71]
	v_mfma_f32_16x16x32_bf16 v[64:67], v[178:181], v[214:217], v[64:67]
	s_setprio 0
	s_barrier
	s_add_i32 s57, s41, s0
	s_mov_b32 m0, s57
	ds_read_b128 v[182:185], v153 offset:16384
	ds_read_b128 v[186:189], v153 offset:17408
	ds_read_b128 v[194:197], v153 offset:18432
	ds_read_b128 v[198:201], v153 offset:19456
	global_load_lds_dwordx4 v130, s[28:29]
	s_add_i32 m0, s57, 0x2000
	s_add_u32 s58, s28, 0x100000
	s_addc_u32 s59, s29, 0
	s_add_i32 s57, s42, s0
	global_load_lds_dwordx4 v134, s[28:29]
	s_mov_b32 m0, s57
	ds_read_b128 v[214:217], v153 offset:23552
	global_load_lds_dwordx4 v130, s[58:59]
	s_add_i32 m0, s57, 0x2000
	ds_read_b128 v[210:213], v153 offset:22528
	global_load_lds_dwordx4 v134, s[58:59]
	s_mov_b32 m0, s1
	ds_read_b128 v[206:209], v153 offset:21504
	global_load_lds_dwordx4 v128, s[34:35]
	s_mov_b32 m0, s31
	ds_read_b128 v[202:205], v153 offset:20480
	global_load_lds_dwordx4 v132, s[34:35]
	s_waitcnt vmcnt(8)
	s_waitcnt lgkmcnt(0)
	s_barrier
	s_setprio 1
	s_waitcnt lgkmcnt(0)
	v_mfma_f32_16x16x32_bf16 v[60:63], v[144:147], v[182:185], v[60:63]
	v_mfma_f32_16x16x32_bf16 v[56:59], v[158:161], v[182:185], v[56:59]
	v_mfma_f32_16x16x32_bf16 v[44:47], v[144:147], v[194:197], v[44:47]
	v_mfma_f32_16x16x32_bf16 v[40:43], v[158:161], v[194:197], v[40:43]
	v_mfma_f32_16x16x32_bf16 v[28:31], v[144:147], v[202:205], v[28:31]
	v_mfma_f32_16x16x32_bf16 v[24:27], v[158:161], v[202:205], v[24:27]
	v_mfma_f32_16x16x32_bf16 v[12:15], v[144:147], v[210:213], v[12:15]
	v_mfma_f32_16x16x32_bf16 v[8:11], v[158:161], v[210:213], v[8:11]
	v_mfma_f32_16x16x32_bf16 v[60:63], v[154:157], v[186:189], v[60:63]
	v_mfma_f32_16x16x32_bf16 v[56:59], v[162:165], v[186:189], v[56:59]
	v_mfma_f32_16x16x32_bf16 v[44:47], v[154:157], v[198:201], v[44:47]
	v_mfma_f32_16x16x32_bf16 v[40:43], v[162:165], v[198:201], v[40:43]
	v_mfma_f32_16x16x32_bf16 v[28:31], v[154:157], v[206:209], v[28:31]
	v_mfma_f32_16x16x32_bf16 v[24:27], v[162:165], v[206:209], v[24:27]
	v_mfma_f32_16x16x32_bf16 v[12:15], v[154:157], v[214:217], v[12:15]
	v_mfma_f32_16x16x32_bf16 v[8:11], v[162:165], v[214:217], v[8:11]
	s_setprio 0
	s_setprio 1
	v_mfma_f32_16x16x32_bf16 v[52:55], v[166:169], v[182:185], v[52:55]
	v_mfma_f32_16x16x32_bf16 v[48:51], v[174:177], v[182:185], v[48:51]
	v_mfma_f32_16x16x32_bf16 v[36:39], v[166:169], v[194:197], v[36:39]
	v_mfma_f32_16x16x32_bf16 v[32:35], v[174:177], v[194:197], v[32:35]
	v_mfma_f32_16x16x32_bf16 v[20:23], v[166:169], v[202:205], v[20:23]
	v_mfma_f32_16x16x32_bf16 v[16:19], v[174:177], v[202:205], v[16:19]
	v_mfma_f32_16x16x32_bf16 v[4:7], v[166:169], v[210:213], v[4:7]
	v_mfma_f32_16x16x32_bf16 v[0:3], v[174:177], v[210:213], v[0:3]
	v_mfma_f32_16x16x32_bf16 v[52:55], v[170:173], v[186:189], v[52:55]
	v_mfma_f32_16x16x32_bf16 v[48:51], v[178:181], v[186:189], v[48:51]
	v_mfma_f32_16x16x32_bf16 v[36:39], v[170:173], v[198:201], v[36:39]
	v_mfma_f32_16x16x32_bf16 v[32:35], v[178:181], v[198:201], v[32:35]
	v_mfma_f32_16x16x32_bf16 v[20:23], v[170:173], v[206:209], v[20:23]
	v_mfma_f32_16x16x32_bf16 v[16:19], v[178:181], v[206:209], v[16:19]
	v_mfma_f32_16x16x32_bf16 v[4:7], v[170:173], v[214:217], v[4:7]
	v_mfma_f32_16x16x32_bf16 v[0:3], v[178:181], v[214:217], v[0:3]
	s_setprio 0
	s_barrier
; #define PG8_STAGE(bufoff, gbase, voff) do { _Pragma("unroll") for (int _i = 0; _i < 2; ++_i) \
;         __builtin_amdgcn_global_load_lds((const unsigned*)((const char*)(gbase) + (voff)[_i]), (PG8_LAS unsigned*)(lds + (bufoff) + ldsw + _i * 8192), 16, 0, 0); } while (0)
; #define PG8_LDA(dst, b, h) do { _Pragma("unroll") for (int m = 0; m < 4; ++m) _Pragma("unroll") for (int k = 0; k < 2; ++k) dst[m][k] = *(const PG8_LAS bf16x8*)(lds + PG8_SA(b, h) + aoff + m * 2048 + k * 1024); } while (0)
; #define PG8_LDB(dst, b, h) do { _Pragma("unroll") for (int n = 0; n < 2; ++n) _Pragma("unroll") for (int k = 0; k < 2; ++k) dst[n][k] = *(const PG8_LAS bf16x8*)(lds + PG8_SB(b, h) + boff + n * 2048 + k * 1024); } while (0)
; #define PG8_MMA(ai, bj, At, Bt) do { __builtin_amdgcn_s_setprio(1); _Pragma("unroll") for (int m = 0; m < 4; ++m) _Pragma("unroll") for (int n = 0; n < 2; ++n) _Pragma("unroll") for (int k = 0; k < 2; ++k) \
;         acc[ai][bj][m][n] = __builtin_amdgcn_mfma_f32_16x16x32_bf16(Bt[n][k], At[m][k], acc[ai][bj][m][n], 0, 0, 0); __builtin_amdgcn_s_setprio(0); } while (0)
; #define PG8_WAIT_V(n) asm volatile("s_waitcnt vmcnt(" #n ")" ::: "memory")
; #define PG8_WAIT_L(n) asm volatile("s_waitcnt lgkmcnt(" #n ")" ::: "memory")
; #define PG8_BAR __builtin_amdgcn_s_barrier()
; #define PG8_SCHED __builtin_amdgcn_sched_barrier(0)
; template <class Epi, class Sched, bool ALIGN_EPI = false, bool SP2 = false>
; __device__ __forceinline__ void gemm_phase(PG8_LAS unsigned char* lds, const Gemm g, const Sched& S, const Epi& E) {
;     ...
;             PG8_LDB(B0, 1, 0); PG8_LDB(B1, 1, 1); PG8_SCHED; PG8_LDA(At, 1, 0); PG8_STAGE(PG8_SA(0, 1), a2 + hstep, voffA);
;             PG8_WAIT_V(8); PG8_WAIT_L(0); PG8_BAR; PG8_MMA(0, 0, At, B0); PG8_MMA(0, 1, At, B1); PG8_BAR; PG8_SCHED;
;             PG8_LDA(At, 1, 1); PG8_STAGE(PG8_SB(1, 0), b3, voffB); PG8_STAGE(PG8_SB(1, 1), b3 + hstep, voffB); PG8_STAGE(PG8_SA(1, 0), a3, voffA);
;             PG8_WAIT_V(8); PG8_WAIT_L(0); PG8_BAR; PG8_MMA(1, 0, At, B0); PG8_MMA(1, 1, At, B1); PG8_BAR; PG8_SCHED;
	s_add_i32 s57, 0, 0x18000
	s_add_i32 s58, 0, 0x1c000
	v_add_u32_e32 v162, s57, v149
	v_add_u32_e32 v178, s58, v149
	ds_read_b128 v[144:147], v162
	ds_read_b128 v[154:157], v162 offset:1024
	ds_read_b128 v[158:161], v162 offset:2048
	ds_read_b128 v[162:165], v162 offset:3072
	ds_read_b128 v[166:169], v178
	ds_read_b128 v[170:173], v178 offset:1024
	ds_read_b128 v[174:177], v178 offset:2048
	ds_read_b128 v[178:181], v178 offset:3072
	s_add_u32 s34, s34, 0x100000
	s_addc_u32 s35, s35, 0
	s_mov_b32 m0, s36
	ds_read_b128 v[182:185], v153 offset:32768
	ds_read_b128 v[186:189], v153 offset:33792
	ds_read_b128 v[194:197], v153 offset:34816
	ds_read_b128 v[198:201], v153 offset:35840
	ds_read_b128 v[202:205], v153 offset:36864
	ds_read_b128 v[206:209], v153 offset:37888
	ds_read_b128 v[210:213], v153 offset:38912
	global_load_lds_dwordx4 v128, s[34:35]
	s_mov_b32 m0, s37
	ds_read_b128 v[214:217], v153 offset:39936
	global_load_lds_dwordx4 v132, s[34:35]
	s_waitcnt vmcnt(8)
	s_waitcnt lgkmcnt(0)
	s_barrier
	s_setprio 1
	s_waitcnt lgkmcnt(0)
	v_mfma_f32_16x16x32_bf16 v[124:127], v[144:147], v[182:185], v[124:127]
	v_mfma_f32_16x16x32_bf16 v[120:123], v[158:161], v[182:185], v[120:123]
	v_mfma_f32_16x16x32_bf16 v[108:111], v[144:147], v[194:197], v[108:111]
	v_mfma_f32_16x16x32_bf16 v[104:107], v[158:161], v[194:197], v[104:107]
	v_mfma_f32_16x16x32_bf16 v[92:95], v[144:147], v[202:205], v[92:95]
	v_mfma_f32_16x16x32_bf16 v[88:91], v[158:161], v[202:205], v[88:91]
	v_mfma_f32_16x16x32_bf16 v[76:79], v[144:147], v[210:213], v[76:79]
	v_mfma_f32_16x16x32_bf16 v[72:75], v[158:161], v[210:213], v[72:75]
	v_mfma_f32_16x16x32_bf16 v[124:127], v[154:157], v[186:189], v[124:127]
	v_mfma_f32_16x16x32_bf16 v[120:123], v[162:165], v[186:189], v[120:123]
	v_mfma_f32_16x16x32_bf16 v[108:111], v[154:157], v[198:201], v[108:111]
	v_mfma_f32_16x16x32_bf16 v[104:107], v[162:165], v[198:201], v[104:107]
	v_mfma_f32_16x16x32_bf16 v[92:95], v[154:157], v[206:209], v[92:95]
	v_mfma_f32_16x16x32_bf16 v[88:91], v[162:165], v[206:209], v[88:91]
	v_mfma_f32_16x16x32_bf16 v[76:79], v[154:157], v[214:217], v[76:79]
	v_mfma_f32_16x16x32_bf16 v[72:75], v[162:165], v[214:217], v[72:75]
	s_setprio 0
	s_setprio 1
	v_mfma_f32_16x16x32_bf16 v[116:119], v[166:169], v[182:185], v[116:119]
	v_mfma_f32_16x16x32_bf16 v[112:115], v[174:177], v[182:185], v[112:115]
	v_mfma_f32_16x16x32_bf16 v[100:103], v[166:169], v[194:197], v[100:103]
	v_mfma_f32_16x16x32_bf16 v[96:99], v[174:177], v[194:197], v[96:99]
	v_mfma_f32_16x16x32_bf16 v[84:87], v[166:169], v[202:205], v[84:87]
	v_mfma_f32_16x16x32_bf16 v[80:83], v[174:177], v[202:205], v[80:83]
	v_mfma_f32_16x16x32_bf16 v[68:71], v[166:169], v[210:213], v[68:71]
	v_mfma_f32_16x16x32_bf16 v[64:67], v[174:177], v[210:213], v[64:67]
	v_mfma_f32_16x16x32_bf16 v[116:119], v[170:173], v[186:189], v[116:119]
	v_mfma_f32_16x16x32_bf16 v[112:115], v[178:181], v[186:189], v[112:115]
	v_mfma_f32_16x16x32_bf16 v[100:103], v[170:173], v[198:201], v[100:103]
	v_mfma_f32_16x16x32_bf16 v[96:99], v[178:181], v[198:201], v[96:99]
	v_mfma_f32_16x16x32_bf16 v[84:87], v[170:173], v[206:209], v[84:87]
	v_mfma_f32_16x16x32_bf16 v[80:83], v[178:181], v[206:209], v[80:83]
	v_mfma_f32_16x16x32_bf16 v[68:71], v[170:173], v[214:217], v[68:71]
	v_mfma_f32_16x16x32_bf16 v[64:67], v[178:181], v[214:217], v[64:67]
	s_setprio 0
	s_barrier
	s_add_i32 s34, s57, s0
	s_mov_b32 m0, s34
	ds_read_b128 v[182:185], v153 offset:49152
	ds_read_b128 v[186:189], v153 offset:50176
	ds_read_b128 v[194:197], v153 offset:51200
	ds_read_b128 v[198:201], v153 offset:52224
	global_load_lds_dwordx4 v130, vcc
	s_add_i32 m0, s34, 0x2000
	s_add_u32 s28, s28, 0x100080
	s_addc_u32 s29, s29, 0
	s_add_i32 s34, s58, s0
	global_load_lds_dwordx4 v134, vcc
	s_mov_b32 m0, s34
	ds_read_b128 v[214:217], v153 offset:56320
	global_load_lds_dwordx4 v130, s[28:29]
	s_add_i32 m0, s34, 0x2000
	ds_read_b128 v[210:213], v153 offset:55296
	global_load_lds_dwordx4 v134, s[28:29]
	s_mov_b32 m0, s39
	ds_read_b128 v[206:209], v153 offset:54272
	global_load_lds_dwordx4 v128, s[100:101]
	s_mov_b32 m0, s40
	ds_read_b128 v[202:205], v153 offset:53248
	global_load_lds_dwordx4 v132, s[100:101]
	s_waitcnt vmcnt(8)
	s_waitcnt lgkmcnt(0)
	s_barrier
	s_setprio 1
	s_waitcnt lgkmcnt(0)
	v_mfma_f32_16x16x32_bf16 v[60:63], v[144:147], v[182:185], v[60:63]
	v_mfma_f32_16x16x32_bf16 v[56:59], v[158:161], v[182:185], v[56:59]
	v_mfma_f32_16x16x32_bf16 v[44:47], v[144:147], v[194:197], v[44:47]
	v_mfma_f32_16x16x32_bf16 v[40:43], v[158:161], v[194:197], v[40:43]
	v_mfma_f32_16x16x32_bf16 v[28:31], v[144:147], v[202:205], v[28:31]
	v_mfma_f32_16x16x32_bf16 v[24:27], v[158:161], v[202:205], v[24:27]
	v_mfma_f32_16x16x32_bf16 v[12:15], v[144:147], v[210:213], v[12:15]
	v_mfma_f32_16x16x32_bf16 v[8:11], v[158:161], v[210:213], v[8:11]
	v_mfma_f32_16x16x32_bf16 v[60:63], v[154:157], v[186:189], v[60:63]
	v_mfma_f32_16x16x32_bf16 v[56:59], v[162:165], v[186:189], v[56:59]
	v_mfma_f32_16x16x32_bf16 v[44:47], v[154:157], v[198:201], v[44:47]
	v_mfma_f32_16x16x32_bf16 v[40:43], v[162:165], v[198:201], v[40:43]
	v_mfma_f32_16x16x32_bf16 v[28:31], v[154:157], v[206:209], v[28:31]
	v_mfma_f32_16x16x32_bf16 v[24:27], v[162:165], v[206:209], v[24:27]
	v_mfma_f32_16x16x32_bf16 v[12:15], v[154:157], v[214:217], v[12:15]
	v_mfma_f32_16x16x32_bf16 v[8:11], v[162:165], v[214:217], v[8:11]
	s_setprio 0
	s_setprio 1
	v_mfma_f32_16x16x32_bf16 v[52:55], v[166:169], v[182:185], v[52:55]
	v_mfma_f32_16x16x32_bf16 v[48:51], v[174:177], v[182:185], v[48:51]
	v_mfma_f32_16x16x32_bf16 v[36:39], v[166:169], v[194:197], v[36:39]
	v_mfma_f32_16x16x32_bf16 v[32:35], v[174:177], v[194:197], v[32:35]
	v_mfma_f32_16x16x32_bf16 v[20:23], v[166:169], v[202:205], v[20:23]
	v_mfma_f32_16x16x32_bf16 v[16:19], v[174:177], v[202:205], v[16:19]
	v_mfma_f32_16x16x32_bf16 v[4:7], v[166:169], v[210:213], v[4:7]
	v_mfma_f32_16x16x32_bf16 v[0:3], v[174:177], v[210:213], v[0:3]
	v_mfma_f32_16x16x32_bf16 v[52:55], v[170:173], v[186:189], v[52:55]
	v_mfma_f32_16x16x32_bf16 v[48:51], v[178:181], v[186:189], v[48:51]
	v_mfma_f32_16x16x32_bf16 v[36:39], v[170:173], v[198:201], v[36:39]
	v_mfma_f32_16x16x32_bf16 v[32:35], v[178:181], v[198:201], v[32:35]
	v_mfma_f32_16x16x32_bf16 v[20:23], v[170:173], v[206:209], v[20:23]
	v_mfma_f32_16x16x32_bf16 v[16:19], v[178:181], v[206:209], v[16:19]
	v_mfma_f32_16x16x32_bf16 v[4:7], v[170:173], v[214:217], v[4:7]
	v_mfma_f32_16x16x32_bf16 v[0:3], v[178:181], v[214:217], v[0:3]
	s_setprio 0
	s_barrier
	s_add_i32 s56, s56, 2
	s_add_u32 s26, s26, 0x100
	s_addc_u32 s27, s27, 0
	s_add_u32 s50, s50, 0x100
	s_addc_u32 s51, s51, 0
	s_cmp_gt_u32 s56, 61
	s_cbranch_scc0 .LBB0_501
	s_and_b64 vcc, exec, s[14:15]
	s_cbranch_vccz .LBB0_504
	s_barrier
